# GEMM K-loops: flips removed + one static s_setprio 1 for waves 4-7 per K-loop
# baseline (speedup 1.0000x reference)
; #define LAS __attribute__((address_space(3)))
; __global__ void __launch_bounds__(NTHR, 2) mega_fwd(Args A) {
;     extern __shared__ __attribute__((aligned(16))) unsigned char lds_raw[];
;     LAS unsigned char* lds = (LAS unsigned char*)lds_raw;
;     const int G = gridDim.x, bx = blockIdx.x;
;     volatile LAS unsigned* bst = (volatile LAS unsigned*)(lds + LDS_BYTES - 16);
;     if (threadIdx.x < 4) bst[threadIdx.x] = 0u;
;     __syncthreads();
;     XcdBarrier bar; bar.bar = (unsigned*)A.ws; bar.x = 0; bar.st = bst;
;     if (A.coop) bar = xcd_barrier_post((unsigned*)A.ws, bst);
_Z8mega_fwd4Args:
	s_load_dwordx8 s[4:11], s[0:1], 0x80
	v_readfirstlane_b32 s101, v0
	s_nop 3
	s_and_b32 s101, s101, 0x3ff
	s_lshr_b32 s101, s101, 8
	s_mov_b32 s67, s2
	s_load_dwordx2 s[2:3], s[0:1], 0xa0
	v_and_b32_e32 v240, 0x3ff, v0
	v_cmp_gt_u32_e32 vcc, 4, v240
	s_waitcnt lgkmcnt(0)
	v_writelane_b32 v252, s4, 0
	s_nop 1
	v_writelane_b32 v252, s5, 1
	v_writelane_b32 v252, s6, 2
	v_writelane_b32 v252, s7, 3
	v_writelane_b32 v252, s8, 4
	v_writelane_b32 v252, s9, 5
	v_writelane_b32 v252, s10, 6
	v_writelane_b32 v252, s11, 7
	v_writelane_b32 v252, s2, 8
	s_nop 1
	v_writelane_b32 v252, s3, 9
	s_load_dwordx4 s[40:43], s[0:1], 0xa8
	s_load_dword s2, s[0:1], 0xb8
	s_waitcnt lgkmcnt(0)
	v_writelane_b32 v252, s2, 10
	s_add_u32 s2, s0, 0xb8
	s_addc_u32 s3, s1, 0
	v_writelane_b32 v252, s2, 11
	s_nop 1
	v_writelane_b32 v252, s3, 12
	s_and_saveexec_b64 s[4:5], vcc
	v_lshl_add_u32 v1, v240, 2, 0
	v_add_u32_e32 v1, 0x21ff0, v1
	v_mov_b32_e32 v2, 0
	ds_write_b32 v1, v2
	s_or_b64 exec, exec, s[4:5]
	s_cmp_lg_u32 s40, 0
	s_cselect_b64 s[4:5], -1, 0
	v_writelane_b32 v252, s4, 13
	s_mov_b32 s2, 0
	s_cmp_eq_u32 s40, 0
	v_writelane_b32 v252, s5, 14
	v_cmp_eq_u32_e32 vcc, 0, v240
	s_waitcnt lgkmcnt(0)
	s_barrier
	s_cbranch_scc1 .LBB0_7
	s_getreg_b32 s2, hwreg(HW_REG_XCC_ID, 0, 4)
	s_and_b32 s2, s2, 15
	s_and_saveexec_b64 s[4:5], vcc
	s_cbranch_execz .LBB0_6
	s_mov_b64 s[6:7], exec
	v_mbcnt_lo_u32_b32 v1, s6, 0
	v_mbcnt_hi_u32_b32 v1, s7, v1
	v_cmp_eq_u32_e32 vcc, 0, v1
	s_and_b64 s[8:9], exec, vcc
	s_mov_b64 exec, s[8:9]
	s_cbranch_execz .LBB0_6
	s_bcnt1_i32_b64 s6, s[6:7]
	v_mov_b32_e32 v2, s6
	s_load_dwordx2 s[6:7], s[0:1], 0xa0
	s_lshl_b32 s3, s2, 8
	v_mov_b32_e32 v1, s3
	s_waitcnt lgkmcnt(0)
	global_atomic_add v1, v2, s[6:7] offset:1024

; #define PG8_STAGE(bufoff, gbase, voff) do { _Pragma("unroll") for (int _i = 0; _i < 2; ++_i) \
;         __builtin_amdgcn_global_load_lds((const unsigned*)((const char*)(gbase) + (voff)[_i]), (PG8_LAS unsigned*)(lds + (bufoff) + ldsw + _i * 8192), 16, 0, 0); } while (0)
; #define PG8_LDA(dst, b, h) do { _Pragma("unroll") for (int m = 0; m < 4; ++m) _Pragma("unroll") for (int k = 0; k < 2; ++k) dst[m][k] = *(const PG8_LAS bf16x8*)(lds + PG8_SA(b, h) + aoff + m * 2048 + k * 1024); } while (0)
; #define PG8_LDB(dst, b, h) do { _Pragma("unroll") for (int n = 0; n < 2; ++n) _Pragma("unroll") for (int k = 0; k < 2; ++k) dst[n][k] = *(const PG8_LAS bf16x8*)(lds + PG8_SB(b, h) + boff + n * 2048 + k * 1024); } while (0)
; #define PG8_WAIT_V(n) asm volatile("s_waitcnt vmcnt(" #n ")" ::: "memory")
; #define PG8_WAIT_L(n) asm volatile("s_waitcnt lgkmcnt(" #n ")" ::: "memory")
; #define PG8_BAR __builtin_amdgcn_s_barrier()
; #define PG8_SCHED __builtin_amdgcn_sched_barrier(0)
; template <class Epi, class Sched, bool ALIGN_EPI = false, bool SP2 = false>
; __device__ __forceinline__ void gemm_phase(PG8_LAS unsigned char* lds, const Gemm g, const Sched& S, const Epi& E) {
;     ...
;         const char* nA = has_next ? (const char*)g.A + (size_t)nxt.pm * tstep : cA; const char* nB = has_next ? (const char*)g.Bt + (size_t)nxt.pn * tstep : cB;
;         for (int t = 0; t < nt; t += 2) {
;             const bool last = (t == nt - 2);
;             const char* a1 = cA + (size_t)(t + 1) * kstep;
;             const char* a2 = last ? nA : cA + (size_t)(t + 2) * kstep; const char* b2 = last ? nB : cB + (size_t)(t + 2) * kstep;
;             const char* a3 = a2 + kstep; const char* b3 = b2 + kstep;
;             if (last && has_next) S.a_ready(nxt);
;             if constexpr (SP2) {
;             PG8_LDB(B0, 0, 0); PG8_LDB(B1, 0, 1); PG8_SCHED; PG8_LDA(At, 0, 0); PG8_STAGE(PG8_SA(1, 1), a1 + hstep, voffA);
;             PG8_WAIT_V(8); PG8_WAIT_L(0); PG8_BAR; PG8_MMA(0, 0, At, B0); PG8_MMA(0, 1, At, B1); PG8_BAR; PG8_SCHED;
;     ...
; #pragma unroll
;         for (int a = 0; a < 2; ++a)
; #pragma unroll
;             for (int b = 0; b < 2; ++b)
; #pragma unroll
;                 for (int m = 0; m < 4; ++m)
; #pragma unroll
;                     for (int n = 0; n < 2; ++n) acc[a][b][m][n] = (f32x4){0.f, 0.f, 0.f, 0.f};
.LBB0_142:
	s_ashr_i32 s51, s50, 31
	s_lshl_b64 s[34:35], s[50:51], 19
	s_add_u32 s52, s60, s34
	s_addc_u32 s53, s61, s35
	s_and_b64 s[34:35], s[0:1], exec
	s_cselect_b32 s31, s53, s57
	s_cselect_b32 s33, s52, s56
	s_ashr_i32 s49, s48, 31
	s_lshl_b64 s[34:35], s[48:49], 19
	s_add_u32 s54, s3, s34
	s_addc_u32 s55, s10, s35
	s_and_b64 s[34:35], s[0:1], exec
	s_cselect_b32 s34, s55, s5
	s_cselect_b32 s35, s54, s4
	s_add_u32 s49, s4, 0x100
	s_addc_u32 s51, s5, 0
	s_add_u32 s4, s56, 0x40080
	v_mov_b32_e32 v0, 0
	s_addc_u32 s5, s57, 0
	s_mov_b32 s62, -2
	v_mov_b32_e32 v1, v0
	v_mov_b32_e32 v2, v0
	v_mov_b32_e32 v3, v0
	v_mov_b32_e32 v4, v0
	v_mov_b32_e32 v5, v0
	v_mov_b32_e32 v6, v0
	v_mov_b32_e32 v7, v0
	v_mov_b32_e32 v12, v0
	v_mov_b32_e32 v13, v0
	v_mov_b32_e32 v14, v0
	v_mov_b32_e32 v15, v0
	v_mov_b32_e32 v20, v0
	v_mov_b32_e32 v21, v0
	v_mov_b32_e32 v22, v0
	v_mov_b32_e32 v23, v0
	v_mov_b32_e32 v28, v0
	v_mov_b32_e32 v29, v0
	v_mov_b32_e32 v30, v0
	v_mov_b32_e32 v31, v0
	s_waitcnt vmcnt(0)
	v_mov_b32_e32 v36, v0
	v_mov_b32_e32 v37, v0
	v_mov_b32_e32 v38, v0
	v_mov_b32_e32 v39, v0
	v_mov_b32_e32 v44, v0
	v_mov_b32_e32 v45, v0
	v_mov_b32_e32 v46, v0
	v_mov_b32_e32 v47, v0
	v_mov_b32_e32 v52, v0
	v_mov_b32_e32 v53, v0
	v_mov_b32_e32 v54, v0
	v_mov_b32_e32 v55, v0
	v_mov_b32_e32 v8, v0
	v_mov_b32_e32 v9, v0
	v_mov_b32_e32 v10, v0
	v_mov_b32_e32 v11, v0
	v_mov_b32_e32 v16, v0
	v_mov_b32_e32 v17, v0
	v_mov_b32_e32 v18, v0
	v_mov_b32_e32 v19, v0
	v_mov_b32_e32 v24, v0
	v_mov_b32_e32 v25, v0
	v_mov_b32_e32 v26, v0
	v_mov_b32_e32 v27, v0
	v_mov_b32_e32 v32, v0
	v_mov_b32_e32 v33, v0
	v_mov_b32_e32 v34, v0
	v_mov_b32_e32 v35, v0
	v_mov_b32_e32 v40, v0
	v_mov_b32_e32 v41, v0
	v_mov_b32_e32 v42, v0
	v_mov_b32_e32 v43, v0
	v_mov_b32_e32 v48, v0
	v_mov_b32_e32 v49, v0
	v_mov_b32_e32 v50, v0
	v_mov_b32_e32 v51, v0
	v_mov_b32_e32 v56, v0
	v_mov_b32_e32 v57, v0
	v_mov_b32_e32 v58, v0
	v_mov_b32_e32 v59, v0
	v_mov_b32_e32 v60, v0
	v_mov_b32_e32 v61, v0
	v_mov_b32_e32 v62, v0
	v_mov_b32_e32 v63, v0
	v_mov_b32_e32 v64, v0
	v_mov_b32_e32 v65, v0
	v_mov_b32_e32 v66, v0
	v_mov_b32_e32 v67, v0
	v_mov_b32_e32 v68, v0
	v_mov_b32_e32 v69, v0
	v_mov_b32_e32 v70, v0
	v_mov_b32_e32 v71, v0
	v_mov_b32_e32 v80, v0
	v_mov_b32_e32 v81, v0
	v_mov_b32_e32 v82, v0
	v_mov_b32_e32 v83, v0
	v_mov_b32_e32 v84, v0
	v_mov_b32_e32 v85, v0
	v_mov_b32_e32 v86, v0
	v_mov_b32_e32 v87, v0
	v_mov_b32_e32 v96, v0
	v_mov_b32_e32 v97, v0
	v_mov_b32_e32 v98, v0
	v_mov_b32_e32 v99, v0
	v_mov_b32_e32 v100, v0
	v_mov_b32_e32 v101, v0
	v_mov_b32_e32 v102, v0
	v_mov_b32_e32 v103, v0
	v_mov_b32_e32 v112, v0
	v_mov_b32_e32 v113, v0
	v_mov_b32_e32 v114, v0
	v_mov_b32_e32 v115, v0
	v_mov_b32_e32 v116, v0
	v_mov_b32_e32 v117, v0
	v_mov_b32_e32 v118, v0
	v_mov_b32_e32 v119, v0
	v_mov_b32_e32 v72, v0
	v_mov_b32_e32 v73, v0
	v_mov_b32_e32 v74, v0
	v_mov_b32_e32 v75, v0
	v_mov_b32_e32 v76, v0
	v_mov_b32_e32 v77, v0
	v_mov_b32_e32 v78, v0
	v_mov_b32_e32 v79, v0
	v_mov_b32_e32 v88, v0
	v_mov_b32_e32 v89, v0
	v_mov_b32_e32 v90, v0
	v_mov_b32_e32 v91, v0
	v_mov_b32_e32 v92, v0
	v_mov_b32_e32 v93, v0
	v_mov_b32_e32 v94, v0
	v_mov_b32_e32 v95, v0
	v_mov_b32_e32 v104, v0
	v_mov_b32_e32 v105, v0
	v_mov_b32_e32 v106, v0
	v_mov_b32_e32 v107, v0
	v_mov_b32_e32 v108, v0
	v_mov_b32_e32 v109, v0
	v_mov_b32_e32 v110, v0
	v_mov_b32_e32 v111, v0
	v_mov_b32_e32 v120, v0
	v_mov_b32_e32 v121, v0
	v_mov_b32_e32 v122, v0
	v_mov_b32_e32 v123, v0
	v_mov_b32_e32 v124, v0
	v_mov_b32_e32 v125, v0
	v_mov_b32_e32 v126, v0
	v_mov_b32_e32 v127, v0
	s_cmp_eq_u32 s101, 0
	s_cbranch_scc1 .Lsp_skip0
	s_setprio 1
.Lsp_skip0:
.LBB0_143:
	s_add_u32 s56, s4, 0xfffc0080
	s_addc_u32 s57, s5, -1
	s_add_i32 s63, 0, 0x10000
	s_cmp_eq_u32 s62, 12
	s_cselect_b32 s59, s31, s57
	s_cselect_b32 s58, s33, s56
	s_cselect_b32 s57, s34, s51
	s_cselect_b32 s56, s35, s49
	s_add_i32 s66, 0, 0x14000
	v_add_u32_e32 v140, s63, v249
	v_add_u32_e32 v156, s66, v249
	ds_read_b128 v[128:131], v140
	ds_read_b128 v[132:135], v140 offset:1024
	ds_read_b128 v[136:139], v140 offset:2048
	ds_read_b128 v[140:143], v140 offset:3072
	ds_read_b128 v[144:147], v156
	ds_read_b128 v[148:151], v156 offset:1024
	ds_read_b128 v[152:155], v156 offset:2048
	ds_read_b128 v[156:159], v156 offset:3072
	v_lshl_add_u64 v[178:179], s[4:5], 0, v[206:207]
	s_add_i32 m0, s11, 0xc000
	ds_read_b128 v[160:163], v245
	ds_read_b128 v[164:167], v245 offset:1024
	ds_read_b128 v[168:171], v245 offset:2048
	ds_read_b128 v[172:175], v245 offset:3072
	ds_read_b128 v[208:211], v245 offset:4096
	ds_read_b128 v[212:215], v245 offset:5120
	ds_read_b128 v[216:219], v245 offset:6144
	ds_read_b128 v[220:223], v245 offset:7168
	global_load_lds_dwordx4 v[178:179], off
	v_lshl_add_u64 v[178:179], s[4:5], 0, v[204:205]
	s_add_i32 m0, s11, 0xe000
	s_nop 0
	global_load_lds_dwordx4 v[178:179], off
	s_waitcnt vmcnt(8)
	s_waitcnt lgkmcnt(0)
	s_barrier
; #define PG8_STAGE(bufoff, gbase, voff) do { _Pragma("unroll") for (int _i = 0; _i < 2; ++_i) \
;         __builtin_amdgcn_global_load_lds((const unsigned*)((const char*)(gbase) + (voff)[_i]), (PG8_LAS unsigned*)(lds + (bufoff) + ldsw + _i * 8192), 16, 0, 0); } while (0)
; #define PG8_LDA(dst, b, h) do { _Pragma("unroll") for (int m = 0; m < 4; ++m) _Pragma("unroll") for (int k = 0; k < 2; ++k) dst[m][k] = *(const PG8_LAS bf16x8*)(lds + PG8_SA(b, h) + aoff + m * 2048 + k * 1024); } while (0)
; #define PG8_MMA(ai, bj, At, Bt) do { __builtin_amdgcn_s_setprio(1); _Pragma("unroll") for (int m = 0; m < 4; ++m) _Pragma("unroll") for (int n = 0; n < 2; ++n) _Pragma("unroll") for (int k = 0; k < 2; ++k) \
;         acc[ai][bj][m][n] = __builtin_amdgcn_mfma_f32_16x16x32_bf16(Bt[n][k], At[m][k], acc[ai][bj][m][n], 0, 0, 0); __builtin_amdgcn_s_setprio(0); } while (0)
; #define PG8_WAIT_V(n) asm volatile("s_waitcnt vmcnt(" #n ")" ::: "memory")
; #define PG8_WAIT_L(n) asm volatile("s_waitcnt lgkmcnt(" #n ")" ::: "memory")
; #define PG8_BAR __builtin_amdgcn_s_barrier()
; #define PG8_SCHED __builtin_amdgcn_sched_barrier(0)
; template <class Epi, class Sched, bool ALIGN_EPI = false, bool SP2 = false>
; __device__ __forceinline__ void gemm_phase(PG8_LAS unsigned char* lds, const Gemm g, const Sched& S, const Epi& E) {
;     ...
;             PG8_WAIT_V(8); PG8_WAIT_L(0); PG8_BAR; PG8_MMA(0, 0, At, B0); PG8_MMA(0, 1, At, B1); PG8_BAR; PG8_SCHED;
;             PG8_LDA(At, 0, 1); PG8_STAGE(PG8_SB(0, 0), b2, voffB); PG8_STAGE(PG8_SB(0, 1), b2 + hstep, voffB); PG8_STAGE(PG8_SA(0, 0), a2, voffA);
;             PG8_WAIT_V(8); PG8_WAIT_L(0); PG8_BAR; PG8_MMA(1, 0, At, B0); PG8_MMA(1, 1, At, B1); PG8_BAR; PG8_SCHED;
	s_waitcnt lgkmcnt(0)
	v_mfma_f32_16x16x32_bf16 v[124:127], v[128:131], v[160:163], v[124:127]
	v_mfma_f32_16x16x32_bf16 v[120:123], v[136:139], v[160:163], v[120:123]
	v_mfma_f32_16x16x32_bf16 v[108:111], v[128:131], v[168:171], v[108:111]
	v_mfma_f32_16x16x32_bf16 v[104:107], v[136:139], v[168:171], v[104:107]
	v_mfma_f32_16x16x32_bf16 v[92:95], v[128:131], v[208:211], v[92:95]
	v_mfma_f32_16x16x32_bf16 v[88:91], v[136:139], v[208:211], v[88:91]
	v_mfma_f32_16x16x32_bf16 v[76:79], v[128:131], v[216:219], v[76:79]
	v_mfma_f32_16x16x32_bf16 v[72:75], v[136:139], v[216:219], v[72:75]
	v_mfma_f32_16x16x32_bf16 v[124:127], v[132:135], v[164:167], v[124:127]
	v_mfma_f32_16x16x32_bf16 v[120:123], v[140:143], v[164:167], v[120:123]
	v_mfma_f32_16x16x32_bf16 v[108:111], v[132:135], v[172:175], v[108:111]
	v_mfma_f32_16x16x32_bf16 v[104:107], v[140:143], v[172:175], v[104:107]
	v_mfma_f32_16x16x32_bf16 v[92:95], v[132:135], v[212:215], v[92:95]
	v_mfma_f32_16x16x32_bf16 v[88:91], v[140:143], v[212:215], v[88:91]
	v_mfma_f32_16x16x32_bf16 v[76:79], v[132:135], v[220:223], v[76:79]
	v_mfma_f32_16x16x32_bf16 v[72:75], v[140:143], v[220:223], v[72:75]
	v_mfma_f32_16x16x32_bf16 v[116:119], v[144:147], v[160:163], v[116:119]
	v_mfma_f32_16x16x32_bf16 v[112:115], v[152:155], v[160:163], v[112:115]
	v_mfma_f32_16x16x32_bf16 v[100:103], v[144:147], v[168:171], v[100:103]
	v_mfma_f32_16x16x32_bf16 v[96:99], v[152:155], v[168:171], v[96:99]
	v_mfma_f32_16x16x32_bf16 v[84:87], v[144:147], v[208:211], v[84:87]
	v_mfma_f32_16x16x32_bf16 v[80:83], v[152:155], v[208:211], v[80:83]
	v_mfma_f32_16x16x32_bf16 v[68:71], v[144:147], v[216:219], v[68:71]
	v_mfma_f32_16x16x32_bf16 v[64:67], v[152:155], v[216:219], v[64:67]
	v_mfma_f32_16x16x32_bf16 v[116:119], v[148:151], v[164:167], v[116:119]
	v_mfma_f32_16x16x32_bf16 v[112:115], v[156:159], v[164:167], v[112:115]
	v_mfma_f32_16x16x32_bf16 v[100:103], v[148:151], v[172:175], v[100:103]
	v_mfma_f32_16x16x32_bf16 v[96:99], v[156:159], v[172:175], v[96:99]
	v_mfma_f32_16x16x32_bf16 v[84:87], v[148:151], v[212:215], v[84:87]
	v_mfma_f32_16x16x32_bf16 v[80:83], v[156:159], v[212:215], v[80:83]
	v_mfma_f32_16x16x32_bf16 v[68:71], v[148:151], v[220:223], v[68:71]
	v_mfma_f32_16x16x32_bf16 v[64:67], v[156:159], v[220:223], v[64:67]
	s_barrier
	s_add_i32 s63, s63, s2
	v_lshl_add_u64 v[178:179], s[56:57], 0, v[198:199]
	s_mov_b32 m0, s63
	ds_read_b128 v[160:163], v245 offset:16384
	ds_read_b128 v[164:167], v245 offset:17408
	ds_read_b128 v[168:171], v245 offset:18432
	ds_read_b128 v[172:175], v245 offset:19456
	ds_read_b128 v[208:211], v245 offset:20480
	ds_read_b128 v[212:215], v245 offset:21504
	ds_read_b128 v[216:219], v245 offset:22528
	ds_read_b128 v[220:223], v245 offset:23552
	global_load_lds_dwordx4 v[178:179], off
	s_add_i32 m0, s63, 0x2000
	s_add_u32 s64, s56, 0x40000
	v_lshl_add_u64 v[224:225], s[56:57], 0, v[194:195]
	s_addc_u32 s65, s57, 0
	s_add_i32 s63, s66, s2
	global_load_lds_dwordx4 v[224:225], off
	v_lshl_add_u64 v[226:227], s[64:65], 0, v[198:199]
	s_mov_b32 m0, s63
	v_lshl_add_u64 v[228:229], s[58:59], 0, v[196:197]
	global_load_lds_dwordx4 v[226:227], off
	v_lshl_add_u64 v[226:227], s[64:65], 0, v[194:195]
	s_add_i32 m0, s63, 0x2000
	s_nop 0
	global_load_lds_dwordx4 v[226:227], off
	v_lshl_add_u64 v[226:227], s[58:59], 0, v[200:201]
	s_mov_b32 m0, s11
	s_nop 0
	global_load_lds_dwordx4 v[226:227], off
	s_mov_b32 m0, s20
	s_nop 0
	global_load_lds_dwordx4 v[228:229], off
	s_waitcnt vmcnt(8)
	s_waitcnt lgkmcnt(0)
	s_barrier
	s_waitcnt lgkmcnt(0)
	v_mfma_f32_16x16x32_bf16 v[60:63], v[128:131], v[160:163], v[60:63]
	v_mfma_f32_16x16x32_bf16 v[56:59], v[136:139], v[160:163], v[56:59]
	v_mfma_f32_16x16x32_bf16 v[48:51], v[128:131], v[168:171], v[48:51]
	v_mfma_f32_16x16x32_bf16 v[40:43], v[136:139], v[168:171], v[40:43]
	v_mfma_f32_16x16x32_bf16 v[32:35], v[128:131], v[208:211], v[32:35]
	v_mfma_f32_16x16x32_bf16 v[24:27], v[136:139], v[208:211], v[24:27]
	v_mfma_f32_16x16x32_bf16 v[16:19], v[128:131], v[216:219], v[16:19]
	v_mfma_f32_16x16x32_bf16 v[8:11], v[136:139], v[216:219], v[8:11]
	v_mfma_f32_16x16x32_bf16 v[60:63], v[132:135], v[164:167], v[60:63]
	v_mfma_f32_16x16x32_bf16 v[56:59], v[140:143], v[164:167], v[56:59]
	v_mfma_f32_16x16x32_bf16 v[48:51], v[132:135], v[172:175], v[48:51]
	v_mfma_f32_16x16x32_bf16 v[40:43], v[140:143], v[172:175], v[40:43]
	v_mfma_f32_16x16x32_bf16 v[32:35], v[132:135], v[212:215], v[32:35]
	v_mfma_f32_16x16x32_bf16 v[24:27], v[140:143], v[212:215], v[24:27]
	v_mfma_f32_16x16x32_bf16 v[16:19], v[132:135], v[220:223], v[16:19]
	v_mfma_f32_16x16x32_bf16 v[8:11], v[140:143], v[220:223], v[8:11]
	v_mfma_f32_16x16x32_bf16 v[52:55], v[144:147], v[160:163], v[52:55]
	v_mfma_f32_16x16x32_bf16 v[44:47], v[152:155], v[160:163], v[44:47]
	v_mfma_f32_16x16x32_bf16 v[36:39], v[144:147], v[168:171], v[36:39]
	v_mfma_f32_16x16x32_bf16 v[28:31], v[152:155], v[168:171], v[28:31]
	v_mfma_f32_16x16x32_bf16 v[20:23], v[144:147], v[208:211], v[20:23]
	v_mfma_f32_16x16x32_bf16 v[12:15], v[152:155], v[208:211], v[12:15]
	v_mfma_f32_16x16x32_bf16 v[4:7], v[144:147], v[216:219], v[4:7]
	v_mfma_f32_16x16x32_bf16 v[0:3], v[152:155], v[216:219], v[0:3]
	v_mfma_f32_16x16x32_bf16 v[52:55], v[148:151], v[164:167], v[52:55]
	v_mfma_f32_16x16x32_bf16 v[44:47], v[156:159], v[164:167], v[44:47]
	v_mfma_f32_16x16x32_bf16 v[36:39], v[148:151], v[172:175], v[36:39]
	v_mfma_f32_16x16x32_bf16 v[28:31], v[156:159], v[172:175], v[28:31]
	v_mfma_f32_16x16x32_bf16 v[20:23], v[148:151], v[212:215], v[20:23]
	v_mfma_f32_16x16x32_bf16 v[12:15], v[156:159], v[212:215], v[12:15]
	v_mfma_f32_16x16x32_bf16 v[4:7], v[148:151], v[220:223], v[4:7]
	v_mfma_f32_16x16x32_bf16 v[0:3], v[156:159], v[220:223], v[0:3]
	s_barrier
; #define PG8_STAGE(bufoff, gbase, voff) do { _Pragma("unroll") for (int _i = 0; _i < 2; ++_i) \
;         __builtin_amdgcn_global_load_lds((const unsigned*)((const char*)(gbase) + (voff)[_i]), (PG8_LAS unsigned*)(lds + (bufoff) + ldsw + _i * 8192), 16, 0, 0); } while (0)
; #define PG8_LDA(dst, b, h) do { _Pragma("unroll") for (int m = 0; m < 4; ++m) _Pragma("unroll") for (int k = 0; k < 2; ++k) dst[m][k] = *(const PG8_LAS bf16x8*)(lds + PG8_SA(b, h) + aoff + m * 2048 + k * 1024); } while (0)
; #define PG8_LDB(dst, b, h) do { _Pragma("unroll") for (int n = 0; n < 2; ++n) _Pragma("unroll") for (int k = 0; k < 2; ++k) dst[n][k] = *(const PG8_LAS bf16x8*)(lds + PG8_SB(b, h) + boff + n * 2048 + k * 1024); } while (0)
; #define PG8_MMA(ai, bj, At, Bt) do { __builtin_amdgcn_s_setprio(1); _Pragma("unroll") for (int m = 0; m < 4; ++m) _Pragma("unroll") for (int n = 0; n < 2; ++n) _Pragma("unroll") for (int k = 0; k < 2; ++k) \
;         acc[ai][bj][m][n] = __builtin_amdgcn_mfma_f32_16x16x32_bf16(Bt[n][k], At[m][k], acc[ai][bj][m][n], 0, 0, 0); __builtin_amdgcn_s_setprio(0); } while (0)
; #define PG8_WAIT_V(n) asm volatile("s_waitcnt vmcnt(" #n ")" ::: "memory")
; #define PG8_WAIT_L(n) asm volatile("s_waitcnt lgkmcnt(" #n ")" ::: "memory")
; #define PG8_BAR __builtin_amdgcn_s_barrier()
; #define PG8_SCHED __builtin_amdgcn_sched_barrier(0)
; template <class Epi, class Sched, bool ALIGN_EPI = false, bool SP2 = false>
; __device__ __forceinline__ void gemm_phase(PG8_LAS unsigned char* lds, const Gemm g, const Sched& S, const Epi& E) {
;     ...
;             PG8_LDB(B0, 1, 0); PG8_LDB(B1, 1, 1); PG8_SCHED; PG8_LDA(At, 1, 0); PG8_STAGE(PG8_SA(0, 1), a2 + hstep, voffA);
;             PG8_WAIT_V(8); PG8_WAIT_L(0); PG8_BAR; PG8_MMA(0, 0, At, B0); PG8_MMA(0, 1, At, B1); PG8_BAR; PG8_SCHED;
	s_add_i32 s63, 0, 0x18000
	s_add_i32 s64, 0, 0x1c000
	v_add_u32_e32 v140, s63, v249
	v_add_u32_e32 v156, s64, v249
	ds_read_b128 v[128:131], v140
	ds_read_b128 v[132:135], v140 offset:1024
	ds_read_b128 v[136:139], v140 offset:2048
	ds_read_b128 v[140:143], v140 offset:3072
	ds_read_b128 v[144:147], v156
	ds_read_b128 v[148:151], v156 offset:1024
	ds_read_b128 v[152:155], v156 offset:2048
	ds_read_b128 v[156:159], v156 offset:3072
	s_add_u32 s58, s58, 0x40000
	s_addc_u32 s59, s59, 0
	s_mov_b32 m0, s21
	v_lshl_add_u64 v[230:231], s[58:59], 0, v[200:201]
	ds_read_b128 v[160:163], v245 offset:32768
	ds_read_b128 v[164:167], v245 offset:33792
	ds_read_b128 v[168:171], v245 offset:34816
	ds_read_b128 v[172:175], v245 offset:35840
	ds_read_b128 v[208:211], v245 offset:36864
	ds_read_b128 v[212:215], v245 offset:37888
	ds_read_b128 v[216:219], v245 offset:38912
	ds_read_b128 v[220:223], v245 offset:39936
	global_load_lds_dwordx4 v[230:231], off
	v_lshl_add_u64 v[230:231], s[58:59], 0, v[196:197]
	s_mov_b32 m0, s22
	s_nop 0
	global_load_lds_dwordx4 v[230:231], off
	s_waitcnt vmcnt(8)
	s_waitcnt lgkmcnt(0)
	s_barrier
	s_waitcnt lgkmcnt(0)
	v_mfma_f32_16x16x32_bf16 v[124:127], v[128:131], v[160:163], v[124:127]
	v_mfma_f32_16x16x32_bf16 v[120:123], v[136:139], v[160:163], v[120:123]
	v_mfma_f32_16x16x32_bf16 v[108:111], v[128:131], v[168:171], v[108:111]
	v_mfma_f32_16x16x32_bf16 v[104:107], v[136:139], v[168:171], v[104:107]
	v_mfma_f32_16x16x32_bf16 v[92:95], v[128:131], v[208:211], v[92:95]
	v_mfma_f32_16x16x32_bf16 v[88:91], v[136:139], v[208:211], v[88:91]
	v_mfma_f32_16x16x32_bf16 v[76:79], v[128:131], v[216:219], v[76:79]
	v_mfma_f32_16x16x32_bf16 v[72:75], v[136:139], v[216:219], v[72:75]
	v_mfma_f32_16x16x32_bf16 v[124:127], v[132:135], v[164:167], v[124:127]
	v_mfma_f32_16x16x32_bf16 v[120:123], v[140:143], v[164:167], v[120:123]
	v_mfma_f32_16x16x32_bf16 v[108:111], v[132:135], v[172:175], v[108:111]
	v_mfma_f32_16x16x32_bf16 v[104:107], v[140:143], v[172:175], v[104:107]
	v_mfma_f32_16x16x32_bf16 v[92:95], v[132:135], v[212:215], v[92:95]
	v_mfma_f32_16x16x32_bf16 v[88:91], v[140:143], v[212:215], v[88:91]
	v_mfma_f32_16x16x32_bf16 v[76:79], v[132:135], v[220:223], v[76:79]
	v_mfma_f32_16x16x32_bf16 v[72:75], v[140:143], v[220:223], v[72:75]
	v_mfma_f32_16x16x32_bf16 v[116:119], v[144:147], v[160:163], v[116:119]
	v_mfma_f32_16x16x32_bf16 v[112:115], v[152:155], v[160:163], v[112:115]
	v_mfma_f32_16x16x32_bf16 v[100:103], v[144:147], v[168:171], v[100:103]
	v_mfma_f32_16x16x32_bf16 v[96:99], v[152:155], v[168:171], v[96:99]
	v_mfma_f32_16x16x32_bf16 v[84:87], v[144:147], v[208:211], v[84:87]
	v_mfma_f32_16x16x32_bf16 v[80:83], v[152:155], v[208:211], v[80:83]
	v_mfma_f32_16x16x32_bf16 v[68:71], v[144:147], v[216:219], v[68:71]
	v_mfma_f32_16x16x32_bf16 v[64:67], v[152:155], v[216:219], v[64:67]
	v_mfma_f32_16x16x32_bf16 v[116:119], v[148:151], v[164:167], v[116:119]
	v_mfma_f32_16x16x32_bf16 v[112:115], v[156:159], v[164:167], v[112:115]
	v_mfma_f32_16x16x32_bf16 v[100:103], v[148:151], v[172:175], v[100:103]
	v_mfma_f32_16x16x32_bf16 v[96:99], v[156:159], v[172:175], v[96:99]
	v_mfma_f32_16x16x32_bf16 v[84:87], v[148:151], v[212:215], v[84:87]
	v_mfma_f32_16x16x32_bf16 v[80:83], v[156:159], v[212:215], v[80:83]
	v_mfma_f32_16x16x32_bf16 v[68:71], v[148:151], v[220:223], v[68:71]
	v_mfma_f32_16x16x32_bf16 v[64:67], v[156:159], v[220:223], v[64:67]
	s_barrier
; #define PG8_STAGE(bufoff, gbase, voff) do { _Pragma("unroll") for (int _i = 0; _i < 2; ++_i) \
;         __builtin_amdgcn_global_load_lds((const unsigned*)((const char*)(gbase) + (voff)[_i]), (PG8_LAS unsigned*)(lds + (bufoff) + ldsw + _i * 8192), 16, 0, 0); } while (0)
; #define PG8_LDA(dst, b, h) do { _Pragma("unroll") for (int m = 0; m < 4; ++m) _Pragma("unroll") for (int k = 0; k < 2; ++k) dst[m][k] = *(const PG8_LAS bf16x8*)(lds + PG8_SA(b, h) + aoff + m * 2048 + k * 1024); } while (0)
; #define PG8_MMA(ai, bj, At, Bt) do { __builtin_amdgcn_s_setprio(1); _Pragma("unroll") for (int m = 0; m < 4; ++m) _Pragma("unroll") for (int n = 0; n < 2; ++n) _Pragma("unroll") for (int k = 0; k < 2; ++k) \
;         acc[ai][bj][m][n] = __builtin_amdgcn_mfma_f32_16x16x32_bf16(Bt[n][k], At[m][k], acc[ai][bj][m][n], 0, 0, 0); __builtin_amdgcn_s_setprio(0); } while (0)
; #define PG8_WAIT_V(n) asm volatile("s_waitcnt vmcnt(" #n ")" ::: "memory")
; #define PG8_WAIT_L(n) asm volatile("s_waitcnt lgkmcnt(" #n ")" ::: "memory")
; #define PG8_BAR __builtin_amdgcn_s_barrier()
; #define PG8_SCHED __builtin_amdgcn_sched_barrier(0)
; template <class Epi, class Sched, bool ALIGN_EPI = false, bool SP2 = false>
; __device__ __forceinline__ void gemm_phase(PG8_LAS unsigned char* lds, const Gemm g, const Sched& S, const Epi& E) {
;     ...
;             PG8_LDA(At, 1, 1); PG8_STAGE(PG8_SB(1, 0), b3, voffB); PG8_STAGE(PG8_SB(1, 1), b3 + hstep, voffB); PG8_STAGE(PG8_SA(1, 0), a3, voffA);
;             PG8_WAIT_V(8); PG8_WAIT_L(0); PG8_BAR; PG8_MMA(1, 0, At, B0); PG8_MMA(1, 1, At, B1); PG8_BAR; PG8_SCHED;
;     ...
;         if constexpr (ALIGN_EPI) { if (wr == 0) PG8_BAR; }
	s_add_i32 s58, s63, s2
	v_lshl_add_u64 v[178:179], v[178:179], 0, s[36:37]
	s_mov_b32 m0, s58
	ds_read_b128 v[160:163], v245 offset:49152
	ds_read_b128 v[164:167], v245 offset:50176
	ds_read_b128 v[168:171], v245 offset:51200
	ds_read_b128 v[172:175], v245 offset:52224
	ds_read_b128 v[208:211], v245 offset:53248
	ds_read_b128 v[212:215], v245 offset:54272
	ds_read_b128 v[216:219], v245 offset:55296
	ds_read_b128 v[220:223], v245 offset:56320
	global_load_lds_dwordx4 v[178:179], off
	s_add_i32 m0, s58, 0x2000
	s_add_u32 s56, s56, 0x40080
	v_lshl_add_u64 v[178:179], v[224:225], 0, s[36:37]
	s_addc_u32 s57, s57, 0
	s_add_i32 s58, s64, s2
	global_load_lds_dwordx4 v[178:179], off
	v_lshl_add_u64 v[178:179], s[56:57], 0, v[198:199]
	s_mov_b32 m0, s58
	s_nop 0
	global_load_lds_dwordx4 v[178:179], off
	v_lshl_add_u64 v[178:179], s[56:57], 0, v[194:195]
	s_add_i32 m0, s58, 0x2000
	s_nop 0
	global_load_lds_dwordx4 v[178:179], off
	v_lshl_add_u64 v[178:179], v[226:227], 0, s[36:37]
	s_mov_b32 m0, s24
	s_nop 0
	global_load_lds_dwordx4 v[178:179], off
	v_lshl_add_u64 v[178:179], v[228:229], 0, s[36:37]
	s_mov_b32 m0, s25
	s_nop 0
	global_load_lds_dwordx4 v[178:179], off
	s_waitcnt vmcnt(8)
	s_waitcnt lgkmcnt(0)
	s_barrier
	s_waitcnt lgkmcnt(0)
	v_mfma_f32_16x16x32_bf16 v[60:63], v[128:131], v[160:163], v[60:63]
	v_mfma_f32_16x16x32_bf16 v[56:59], v[136:139], v[160:163], v[56:59]
	v_mfma_f32_16x16x32_bf16 v[48:51], v[128:131], v[168:171], v[48:51]
	v_mfma_f32_16x16x32_bf16 v[40:43], v[136:139], v[168:171], v[40:43]
	v_mfma_f32_16x16x32_bf16 v[32:35], v[128:131], v[208:211], v[32:35]
	v_mfma_f32_16x16x32_bf16 v[24:27], v[136:139], v[208:211], v[24:27]
	v_mfma_f32_16x16x32_bf16 v[16:19], v[128:131], v[216:219], v[16:19]
	v_mfma_f32_16x16x32_bf16 v[8:11], v[136:139], v[216:219], v[8:11]
	v_mfma_f32_16x16x32_bf16 v[60:63], v[132:135], v[164:167], v[60:63]
	v_mfma_f32_16x16x32_bf16 v[56:59], v[140:143], v[164:167], v[56:59]
	v_mfma_f32_16x16x32_bf16 v[48:51], v[132:135], v[172:175], v[48:51]
	v_mfma_f32_16x16x32_bf16 v[40:43], v[140:143], v[172:175], v[40:43]
	v_mfma_f32_16x16x32_bf16 v[32:35], v[132:135], v[212:215], v[32:35]
	v_mfma_f32_16x16x32_bf16 v[24:27], v[140:143], v[212:215], v[24:27]
	v_mfma_f32_16x16x32_bf16 v[16:19], v[132:135], v[220:223], v[16:19]
	v_mfma_f32_16x16x32_bf16 v[8:11], v[140:143], v[220:223], v[8:11]
	v_mfma_f32_16x16x32_bf16 v[52:55], v[144:147], v[160:163], v[52:55]
	v_mfma_f32_16x16x32_bf16 v[44:47], v[152:155], v[160:163], v[44:47]
	v_mfma_f32_16x16x32_bf16 v[36:39], v[144:147], v[168:171], v[36:39]
	v_mfma_f32_16x16x32_bf16 v[28:31], v[152:155], v[168:171], v[28:31]
	v_mfma_f32_16x16x32_bf16 v[20:23], v[144:147], v[208:211], v[20:23]
	v_mfma_f32_16x16x32_bf16 v[12:15], v[152:155], v[208:211], v[12:15]
	v_mfma_f32_16x16x32_bf16 v[4:7], v[144:147], v[216:219], v[4:7]
	v_mfma_f32_16x16x32_bf16 v[0:3], v[152:155], v[216:219], v[0:3]
	v_mfma_f32_16x16x32_bf16 v[52:55], v[148:151], v[164:167], v[52:55]
	v_mfma_f32_16x16x32_bf16 v[44:47], v[156:159], v[164:167], v[44:47]
	v_mfma_f32_16x16x32_bf16 v[36:39], v[148:151], v[172:175], v[36:39]
	v_mfma_f32_16x16x32_bf16 v[28:31], v[156:159], v[172:175], v[28:31]
	v_mfma_f32_16x16x32_bf16 v[20:23], v[148:151], v[212:215], v[20:23]
	v_mfma_f32_16x16x32_bf16 v[12:15], v[156:159], v[212:215], v[12:15]
	v_mfma_f32_16x16x32_bf16 v[4:7], v[148:151], v[220:223], v[4:7]
	v_mfma_f32_16x16x32_bf16 v[0:3], v[156:159], v[220:223], v[0:3]
	s_barrier
	s_add_i32 s62, s62, 2
	s_add_u32 s49, s49, 0x100
	s_addc_u32 s51, s51, 0
	s_add_u32 s4, s4, 0x100
	s_addc_u32 s5, s5, 0
	s_cmp_gt_u32 s62, 13
	s_cbranch_scc0 .LBB0_143
	s_setprio 0
	s_and_b64 vcc, exec, s[44:45]
	s_cbranch_vccz .LBB0_146
	s_barrier

; #define PG8_STAGE(bufoff, gbase, voff) do { _Pragma("unroll") for (int _i = 0; _i < 2; ++_i) \
;         __builtin_amdgcn_global_load_lds((const unsigned*)((const char*)(gbase) + (voff)[_i]), (PG8_LAS unsigned*)(lds + (bufoff) + ldsw + _i * 8192), 16, 0, 0); } while (0)
; #define PG8_LDA(dst, b, h) do { _Pragma("unroll") for (int m = 0; m < 4; ++m) _Pragma("unroll") for (int k = 0; k < 2; ++k) dst[m][k] = *(const PG8_LAS bf16x8*)(lds + PG8_SA(b, h) + aoff + m * 2048 + k * 1024); } while (0)
; #define PG8_LDB(dst, b, h) do { _Pragma("unroll") for (int n = 0; n < 2; ++n) _Pragma("unroll") for (int k = 0; k < 2; ++k) dst[n][k] = *(const PG8_LAS bf16x8*)(lds + PG8_SB(b, h) + boff + n * 2048 + k * 1024); } while (0)
; #define PG8_WAIT_V(n) asm volatile("s_waitcnt vmcnt(" #n ")" ::: "memory")
; #define PG8_WAIT_L(n) asm volatile("s_waitcnt lgkmcnt(" #n ")" ::: "memory")
; #define PG8_BAR __builtin_amdgcn_s_barrier()
; #define PG8_SCHED __builtin_amdgcn_sched_barrier(0)
; template <class Epi, class Sched, bool ALIGN_EPI = false, bool SP2 = false>
; __device__ __forceinline__ void gemm_phase(PG8_LAS unsigned char* lds, const Gemm g, const Sched& S, const Epi& E) {
;     ...
;         const char* nA = has_next ? (const char*)g.A + (size_t)nxt.pm * tstep : cA; const char* nB = has_next ? (const char*)g.Bt + (size_t)nxt.pn * tstep : cB;
;         for (int t = 0; t < nt; t += 2) {
;             const bool last = (t == nt - 2);
;             const char* a1 = cA + (size_t)(t + 1) * kstep;
;             const char* a2 = last ? nA : cA + (size_t)(t + 2) * kstep; const char* b2 = last ? nB : cB + (size_t)(t + 2) * kstep;
;             const char* a3 = a2 + kstep; const char* b3 = b2 + kstep;
;             if (last && has_next) S.a_ready(nxt);
;             if constexpr (SP2) {
;             PG8_LDB(B0, 0, 0); PG8_LDB(B1, 0, 1); PG8_SCHED; PG8_LDA(At, 0, 0); PG8_STAGE(PG8_SA(1, 1), a1 + hstep, voffA);
;             PG8_WAIT_V(8); PG8_WAIT_L(0); PG8_BAR; PG8_MMA(0, 0, At, B0); PG8_MMA(0, 1, At, B1); PG8_BAR; PG8_SCHED;
;     ...
; #pragma unroll
;         for (int a = 0; a < 2; ++a)
; #pragma unroll
;             for (int b = 0; b < 2; ++b)
; #pragma unroll
;                 for (int m = 0; m < 4; ++m)
; #pragma unroll
;                     for (int n = 0; n < 2; ++n) acc[a][b][m][n] = (f32x4){0.f, 0.f, 0.f, 0.f};
.LBB0_264:
	s_ashr_i32 s49, s48, 31
	s_lshl_b64 s[20:21], s[48:49], 19
	s_add_u32 s50, s60, s20
	s_addc_u32 s51, s61, s21
	s_and_b64 s[20:21], s[38:39], exec
	s_cselect_b32 s11, s51, s17
	s_cselect_b32 s14, s50, s16
	s_ashr_i32 s47, s46, 31
	s_lshl_b64 s[20:21], s[46:47], 19
	s_add_u32 s52, s34, s20
	s_addc_u32 s53, s35, s21
	s_and_b64 s[20:21], s[38:39], exec
	s_cselect_b32 s20, s53, s1
	s_cselect_b32 s21, s52, s0
	s_add_u32 s22, s0, 0x100
	s_addc_u32 s23, s1, 0
	s_add_u32 s0, s16, 0x40080
	v_mov_b32_e32 v0, 0
	s_addc_u32 s1, s17, 0
	s_mov_b32 s24, -2
	v_mov_b32_e32 v1, v0
	v_mov_b32_e32 v2, v0
	v_mov_b32_e32 v3, v0
	v_mov_b32_e32 v4, v0
	v_mov_b32_e32 v5, v0
	v_mov_b32_e32 v6, v0
	v_mov_b32_e32 v7, v0
	s_waitcnt lgkmcnt(0)
	v_mov_b32_e32 v16, v0
	v_mov_b32_e32 v17, v0
	v_mov_b32_e32 v18, v0
	v_mov_b32_e32 v19, v0
	v_mov_b32_e32 v20, v0
	v_mov_b32_e32 v21, v0
	v_mov_b32_e32 v22, v0
	v_mov_b32_e32 v23, v0
	v_mov_b32_e32 v32, v0
	v_mov_b32_e32 v33, v0
	v_mov_b32_e32 v34, v0
	v_mov_b32_e32 v35, v0
	v_mov_b32_e32 v36, v0
	v_mov_b32_e32 v37, v0
	v_mov_b32_e32 v38, v0
	v_mov_b32_e32 v39, v0
	v_mov_b32_e32 v48, v0
	v_mov_b32_e32 v49, v0
	v_mov_b32_e32 v50, v0
	v_mov_b32_e32 v51, v0
	v_mov_b32_e32 v52, v0
	v_mov_b32_e32 v53, v0
	v_mov_b32_e32 v54, v0
	v_mov_b32_e32 v55, v0
	v_mov_b32_e32 v8, v0
	v_mov_b32_e32 v9, v0
	v_mov_b32_e32 v10, v0
	v_mov_b32_e32 v11, v0
	v_mov_b32_e32 v12, v0
	v_mov_b32_e32 v13, v0
	v_mov_b32_e32 v14, v0
	v_mov_b32_e32 v15, v0
	v_mov_b32_e32 v24, v0
	v_mov_b32_e32 v25, v0
	v_mov_b32_e32 v26, v0
	v_mov_b32_e32 v27, v0
	v_mov_b32_e32 v28, v0
	v_mov_b32_e32 v29, v0
	v_mov_b32_e32 v30, v0
	v_mov_b32_e32 v31, v0
	v_mov_b32_e32 v40, v0
	v_mov_b32_e32 v41, v0
	v_mov_b32_e32 v42, v0
	v_mov_b32_e32 v43, v0
	v_mov_b32_e32 v44, v0
	v_mov_b32_e32 v45, v0
	v_mov_b32_e32 v46, v0
	v_mov_b32_e32 v47, v0
	v_mov_b32_e32 v56, v0
	v_mov_b32_e32 v57, v0
	v_mov_b32_e32 v58, v0
	v_mov_b32_e32 v59, v0
	v_mov_b32_e32 v60, v0
	v_mov_b32_e32 v61, v0
	v_mov_b32_e32 v62, v0
	v_mov_b32_e32 v63, v0
	v_mov_b32_e32 v64, v0
	v_mov_b32_e32 v65, v0
	v_mov_b32_e32 v66, v0
	v_mov_b32_e32 v67, v0
	v_mov_b32_e32 v68, v0
	v_mov_b32_e32 v69, v0
	v_mov_b32_e32 v70, v0
	v_mov_b32_e32 v71, v0
	v_mov_b32_e32 v80, v0
	v_mov_b32_e32 v81, v0
	v_mov_b32_e32 v82, v0
	v_mov_b32_e32 v83, v0
	v_mov_b32_e32 v84, v0
	v_mov_b32_e32 v85, v0
	v_mov_b32_e32 v86, v0
	v_mov_b32_e32 v87, v0
	v_mov_b32_e32 v96, v0
	v_mov_b32_e32 v97, v0
	v_mov_b32_e32 v98, v0
	v_mov_b32_e32 v99, v0
	v_mov_b32_e32 v100, v0
	v_mov_b32_e32 v101, v0
	v_mov_b32_e32 v102, v0
	v_mov_b32_e32 v103, v0
	v_mov_b32_e32 v112, v0
	v_mov_b32_e32 v113, v0
	v_mov_b32_e32 v114, v0
	v_mov_b32_e32 v115, v0
	v_mov_b32_e32 v116, v0
	v_mov_b32_e32 v117, v0
	v_mov_b32_e32 v118, v0
	v_mov_b32_e32 v119, v0
	v_mov_b32_e32 v72, v0
	v_mov_b32_e32 v73, v0
	v_mov_b32_e32 v74, v0
	v_mov_b32_e32 v75, v0
	v_mov_b32_e32 v76, v0
	v_mov_b32_e32 v77, v0
	v_mov_b32_e32 v78, v0
	v_mov_b32_e32 v79, v0
	v_mov_b32_e32 v88, v0
	v_mov_b32_e32 v89, v0
	v_mov_b32_e32 v90, v0
	v_mov_b32_e32 v91, v0
	v_mov_b32_e32 v92, v0
	v_mov_b32_e32 v93, v0
	v_mov_b32_e32 v94, v0
	v_mov_b32_e32 v95, v0
	v_mov_b32_e32 v104, v0
	v_mov_b32_e32 v105, v0
	v_mov_b32_e32 v106, v0
	v_mov_b32_e32 v107, v0
	v_mov_b32_e32 v108, v0
	v_mov_b32_e32 v109, v0
	v_mov_b32_e32 v110, v0
	v_mov_b32_e32 v111, v0
	v_mov_b32_e32 v120, v0
	v_mov_b32_e32 v121, v0
	v_mov_b32_e32 v122, v0
	v_mov_b32_e32 v123, v0
	v_mov_b32_e32 v124, v0
	v_mov_b32_e32 v125, v0
	v_mov_b32_e32 v126, v0
	v_mov_b32_e32 v127, v0
	s_cmp_eq_u32 s101, 0
	s_cbranch_scc1 .Lsp_skip1
	s_setprio 1
.Lsp_skip1:
.LBB0_265:
	s_add_u32 s16, s0, 0xfffc0080
	s_addc_u32 s17, s1, -1
	s_add_i32 s25, 0, 0x10000
	s_cmp_eq_u32 s24, 12
	s_cselect_b32 s27, s11, s17
	s_cselect_b32 s26, s14, s16
	v_add_u32_e32 v146, s25, v149
	s_cselect_b32 s17, s20, s23
	s_cselect_b32 s16, s21, s22
	s_add_i32 s30, 0, 0x14000
	ds_read_b128 v[142:145], v146
	ds_read_b128 v[154:157], v146 offset:1024
	ds_read_b128 v[158:161], v146 offset:2048
	ds_read_b128 v[162:165], v146 offset:3072
	v_add_u32_e32 v146, s30, v149
	ds_read_b128 v[166:169], v146
	ds_read_b128 v[170:173], v146 offset:1024
	ds_read_b128 v[194:197], v146 offset:2048
	ds_read_b128 v[198:201], v146 offset:3072
	v_lshl_add_u64 v[146:147], s[0:1], 0, v[140:141]
	s_add_i32 m0, s54, 0xc000
	ds_read_b128 v[202:205], v153
	ds_read_b128 v[206:209], v153 offset:1024
	ds_read_b128 v[210:213], v153 offset:2048
	ds_read_b128 v[214:217], v153 offset:3072
	ds_read_b128 v[218:221], v153 offset:4096
	ds_read_b128 v[222:225], v153 offset:5120
	ds_read_b128 v[226:229], v153 offset:6144
	ds_read_b128 v[230:233], v153 offset:7168
	global_load_lds_dwordx4 v[146:147], off
	v_lshl_add_u64 v[146:147], s[0:1], 0, v[138:139]
	s_add_i32 m0, s54, 0xe000
	s_nop 0
	global_load_lds_dwordx4 v[146:147], off
	s_waitcnt vmcnt(8)
	s_waitcnt lgkmcnt(0)
	s_barrier
; #define PG8_STAGE(bufoff, gbase, voff) do { _Pragma("unroll") for (int _i = 0; _i < 2; ++_i) \
;         __builtin_amdgcn_global_load_lds((const unsigned*)((const char*)(gbase) + (voff)[_i]), (PG8_LAS unsigned*)(lds + (bufoff) + ldsw + _i * 8192), 16, 0, 0); } while (0)
; #define PG8_LDA(dst, b, h) do { _Pragma("unroll") for (int m = 0; m < 4; ++m) _Pragma("unroll") for (int k = 0; k < 2; ++k) dst[m][k] = *(const PG8_LAS bf16x8*)(lds + PG8_SA(b, h) + aoff + m * 2048 + k * 1024); } while (0)
; #define PG8_MMA(ai, bj, At, Bt) do { __builtin_amdgcn_s_setprio(1); _Pragma("unroll") for (int m = 0; m < 4; ++m) _Pragma("unroll") for (int n = 0; n < 2; ++n) _Pragma("unroll") for (int k = 0; k < 2; ++k) \
;         acc[ai][bj][m][n] = __builtin_amdgcn_mfma_f32_16x16x32_bf16(Bt[n][k], At[m][k], acc[ai][bj][m][n], 0, 0, 0); __builtin_amdgcn_s_setprio(0); } while (0)
; #define PG8_WAIT_V(n) asm volatile("s_waitcnt vmcnt(" #n ")" ::: "memory")
; #define PG8_WAIT_L(n) asm volatile("s_waitcnt lgkmcnt(" #n ")" ::: "memory")
; #define PG8_BAR __builtin_amdgcn_s_barrier()
; #define PG8_SCHED __builtin_amdgcn_sched_barrier(0)
; template <class Epi, class Sched, bool ALIGN_EPI = false, bool SP2 = false>
; __device__ __forceinline__ void gemm_phase(PG8_LAS unsigned char* lds, const Gemm g, const Sched& S, const Epi& E) {
;     ...
;             PG8_WAIT_V(8); PG8_WAIT_L(0); PG8_BAR; PG8_MMA(0, 0, At, B0); PG8_MMA(0, 1, At, B1); PG8_BAR; PG8_SCHED;
;             PG8_LDA(At, 0, 1); PG8_STAGE(PG8_SB(0, 0), b2, voffB); PG8_STAGE(PG8_SB(0, 1), b2 + hstep, voffB); PG8_STAGE(PG8_SA(0, 0), a2, voffA);
;             PG8_WAIT_V(8); PG8_WAIT_L(0); PG8_BAR; PG8_MMA(1, 0, At, B0); PG8_MMA(1, 1, At, B1); PG8_BAR; PG8_SCHED;
	s_waitcnt lgkmcnt(0)
	v_mfma_f32_16x16x32_bf16 v[124:127], v[142:145], v[202:205], v[124:127]
	v_mfma_f32_16x16x32_bf16 v[120:123], v[158:161], v[202:205], v[120:123]
	v_mfma_f32_16x16x32_bf16 v[108:111], v[142:145], v[210:213], v[108:111]
	v_mfma_f32_16x16x32_bf16 v[104:107], v[158:161], v[210:213], v[104:107]
	v_mfma_f32_16x16x32_bf16 v[92:95], v[142:145], v[218:221], v[92:95]
	v_mfma_f32_16x16x32_bf16 v[88:91], v[158:161], v[218:221], v[88:91]
	v_mfma_f32_16x16x32_bf16 v[76:79], v[142:145], v[226:229], v[76:79]
	v_mfma_f32_16x16x32_bf16 v[72:75], v[158:161], v[226:229], v[72:75]
	v_mfma_f32_16x16x32_bf16 v[124:127], v[154:157], v[206:209], v[124:127]
	v_mfma_f32_16x16x32_bf16 v[120:123], v[162:165], v[206:209], v[120:123]
	v_mfma_f32_16x16x32_bf16 v[108:111], v[154:157], v[214:217], v[108:111]
	v_mfma_f32_16x16x32_bf16 v[104:107], v[162:165], v[214:217], v[104:107]
	v_mfma_f32_16x16x32_bf16 v[92:95], v[154:157], v[222:225], v[92:95]
	v_mfma_f32_16x16x32_bf16 v[88:91], v[162:165], v[222:225], v[88:91]
	v_mfma_f32_16x16x32_bf16 v[76:79], v[154:157], v[230:233], v[76:79]
	v_mfma_f32_16x16x32_bf16 v[72:75], v[162:165], v[230:233], v[72:75]
	v_mfma_f32_16x16x32_bf16 v[116:119], v[166:169], v[202:205], v[116:119]
	v_mfma_f32_16x16x32_bf16 v[112:115], v[194:197], v[202:205], v[112:115]
	v_mfma_f32_16x16x32_bf16 v[100:103], v[166:169], v[210:213], v[100:103]
	v_mfma_f32_16x16x32_bf16 v[96:99], v[194:197], v[210:213], v[96:99]
	v_mfma_f32_16x16x32_bf16 v[84:87], v[166:169], v[218:221], v[84:87]
	v_mfma_f32_16x16x32_bf16 v[80:83], v[194:197], v[218:221], v[80:83]
	v_mfma_f32_16x16x32_bf16 v[68:71], v[166:169], v[226:229], v[68:71]
	v_mfma_f32_16x16x32_bf16 v[64:67], v[194:197], v[226:229], v[64:67]
	v_mfma_f32_16x16x32_bf16 v[116:119], v[170:173], v[206:209], v[116:119]
	v_mfma_f32_16x16x32_bf16 v[112:115], v[198:201], v[206:209], v[112:115]
	v_mfma_f32_16x16x32_bf16 v[100:103], v[170:173], v[214:217], v[100:103]
	v_mfma_f32_16x16x32_bf16 v[96:99], v[198:201], v[214:217], v[96:99]
	v_mfma_f32_16x16x32_bf16 v[84:87], v[170:173], v[222:225], v[84:87]
	v_mfma_f32_16x16x32_bf16 v[80:83], v[198:201], v[222:225], v[80:83]
	v_mfma_f32_16x16x32_bf16 v[68:71], v[170:173], v[230:233], v[68:71]
	v_mfma_f32_16x16x32_bf16 v[64:67], v[198:201], v[230:233], v[64:67]
	s_barrier
	s_add_i32 s25, s25, s2
	v_lshl_add_u64 v[146:147], s[16:17], 0, v[132:133]
	s_mov_b32 m0, s25
	ds_read_b128 v[202:205], v153 offset:16384
	ds_read_b128 v[206:209], v153 offset:17408
	ds_read_b128 v[210:213], v153 offset:18432
	ds_read_b128 v[214:217], v153 offset:19456
	ds_read_b128 v[218:221], v153 offset:20480
	ds_read_b128 v[222:225], v153 offset:21504
	ds_read_b128 v[226:229], v153 offset:22528
	ds_read_b128 v[230:233], v153 offset:23552
	global_load_lds_dwordx4 v[146:147], off
	s_add_i32 m0, s25, 0x2000
	s_add_u32 s28, s16, 0x40000
	v_lshl_add_u64 v[174:175], s[16:17], 0, v[128:129]
	s_addc_u32 s29, s17, 0
	s_add_i32 s25, s30, s2
	global_load_lds_dwordx4 v[174:175], off
	v_lshl_add_u64 v[178:179], s[28:29], 0, v[132:133]
	s_mov_b32 m0, s25
	v_lshl_add_u64 v[234:235], s[26:27], 0, v[130:131]
	global_load_lds_dwordx4 v[178:179], off
	v_lshl_add_u64 v[178:179], s[28:29], 0, v[128:129]
	s_add_i32 m0, s25, 0x2000
	s_nop 0
	global_load_lds_dwordx4 v[178:179], off
	v_lshl_add_u64 v[178:179], s[26:27], 0, v[134:135]
	s_mov_b32 m0, s54
	s_nop 0
	global_load_lds_dwordx4 v[178:179], off
	s_mov_b32 m0, s55
	s_nop 0
	global_load_lds_dwordx4 v[234:235], off
	s_waitcnt vmcnt(8)
	s_waitcnt lgkmcnt(0)
	s_barrier
	s_waitcnt lgkmcnt(0)
	v_mfma_f32_16x16x32_bf16 v[60:63], v[142:145], v[202:205], v[60:63]
	v_mfma_f32_16x16x32_bf16 v[56:59], v[158:161], v[202:205], v[56:59]
	v_mfma_f32_16x16x32_bf16 v[44:47], v[142:145], v[210:213], v[44:47]
	v_mfma_f32_16x16x32_bf16 v[40:43], v[158:161], v[210:213], v[40:43]
	v_mfma_f32_16x16x32_bf16 v[28:31], v[142:145], v[218:221], v[28:31]
	v_mfma_f32_16x16x32_bf16 v[24:27], v[158:161], v[218:221], v[24:27]
	v_mfma_f32_16x16x32_bf16 v[12:15], v[142:145], v[226:229], v[12:15]
	v_mfma_f32_16x16x32_bf16 v[8:11], v[158:161], v[226:229], v[8:11]
	v_mfma_f32_16x16x32_bf16 v[60:63], v[154:157], v[206:209], v[60:63]
	v_mfma_f32_16x16x32_bf16 v[56:59], v[162:165], v[206:209], v[56:59]
	v_mfma_f32_16x16x32_bf16 v[44:47], v[154:157], v[214:217], v[44:47]
	v_mfma_f32_16x16x32_bf16 v[40:43], v[162:165], v[214:217], v[40:43]
	v_mfma_f32_16x16x32_bf16 v[28:31], v[154:157], v[222:225], v[28:31]
	v_mfma_f32_16x16x32_bf16 v[24:27], v[162:165], v[222:225], v[24:27]
	v_mfma_f32_16x16x32_bf16 v[12:15], v[154:157], v[230:233], v[12:15]
	v_mfma_f32_16x16x32_bf16 v[8:11], v[162:165], v[230:233], v[8:11]
	v_mfma_f32_16x16x32_bf16 v[52:55], v[166:169], v[202:205], v[52:55]
	v_mfma_f32_16x16x32_bf16 v[48:51], v[194:197], v[202:205], v[48:51]
	v_mfma_f32_16x16x32_bf16 v[36:39], v[166:169], v[210:213], v[36:39]
	v_mfma_f32_16x16x32_bf16 v[32:35], v[194:197], v[210:213], v[32:35]
	v_mfma_f32_16x16x32_bf16 v[20:23], v[166:169], v[218:221], v[20:23]
	v_mfma_f32_16x16x32_bf16 v[16:19], v[194:197], v[218:221], v[16:19]
	v_mfma_f32_16x16x32_bf16 v[4:7], v[166:169], v[226:229], v[4:7]
	v_mfma_f32_16x16x32_bf16 v[0:3], v[194:197], v[226:229], v[0:3]
	v_mfma_f32_16x16x32_bf16 v[52:55], v[170:173], v[206:209], v[52:55]
	v_mfma_f32_16x16x32_bf16 v[48:51], v[198:201], v[206:209], v[48:51]
	v_mfma_f32_16x16x32_bf16 v[36:39], v[170:173], v[214:217], v[36:39]
	v_mfma_f32_16x16x32_bf16 v[32:35], v[198:201], v[214:217], v[32:35]
	v_mfma_f32_16x16x32_bf16 v[20:23], v[170:173], v[222:225], v[20:23]
	v_mfma_f32_16x16x32_bf16 v[16:19], v[198:201], v[222:225], v[16:19]
	v_mfma_f32_16x16x32_bf16 v[4:7], v[170:173], v[230:233], v[4:7]
	v_mfma_f32_16x16x32_bf16 v[0:3], v[198:201], v[230:233], v[0:3]
	s_barrier
; #define PG8_STAGE(bufoff, gbase, voff) do { _Pragma("unroll") for (int _i = 0; _i < 2; ++_i) \
;         __builtin_amdgcn_global_load_lds((const unsigned*)((const char*)(gbase) + (voff)[_i]), (PG8_LAS unsigned*)(lds + (bufoff) + ldsw + _i * 8192), 16, 0, 0); } while (0)
; #define PG8_LDA(dst, b, h) do { _Pragma("unroll") for (int m = 0; m < 4; ++m) _Pragma("unroll") for (int k = 0; k < 2; ++k) dst[m][k] = *(const PG8_LAS bf16x8*)(lds + PG8_SA(b, h) + aoff + m * 2048 + k * 1024); } while (0)
; #define PG8_LDB(dst, b, h) do { _Pragma("unroll") for (int n = 0; n < 2; ++n) _Pragma("unroll") for (int k = 0; k < 2; ++k) dst[n][k] = *(const PG8_LAS bf16x8*)(lds + PG8_SB(b, h) + boff + n * 2048 + k * 1024); } while (0)
; #define PG8_MMA(ai, bj, At, Bt) do { __builtin_amdgcn_s_setprio(1); _Pragma("unroll") for (int m = 0; m < 4; ++m) _Pragma("unroll") for (int n = 0; n < 2; ++n) _Pragma("unroll") for (int k = 0; k < 2; ++k) \
;         acc[ai][bj][m][n] = __builtin_amdgcn_mfma_f32_16x16x32_bf16(Bt[n][k], At[m][k], acc[ai][bj][m][n], 0, 0, 0); __builtin_amdgcn_s_setprio(0); } while (0)
; #define PG8_WAIT_V(n) asm volatile("s_waitcnt vmcnt(" #n ")" ::: "memory")
; #define PG8_WAIT_L(n) asm volatile("s_waitcnt lgkmcnt(" #n ")" ::: "memory")
; #define PG8_BAR __builtin_amdgcn_s_barrier()
; #define PG8_SCHED __builtin_amdgcn_sched_barrier(0)
; template <class Epi, class Sched, bool ALIGN_EPI = false, bool SP2 = false>
; __device__ __forceinline__ void gemm_phase(PG8_LAS unsigned char* lds, const Gemm g, const Sched& S, const Epi& E) {
;     ...
;             PG8_LDB(B0, 1, 0); PG8_LDB(B1, 1, 1); PG8_SCHED; PG8_LDA(At, 1, 0); PG8_STAGE(PG8_SA(0, 1), a2 + hstep, voffA);
;             PG8_WAIT_V(8); PG8_WAIT_L(0); PG8_BAR; PG8_MMA(0, 0, At, B0); PG8_MMA(0, 1, At, B1); PG8_BAR; PG8_SCHED;
	s_add_i32 s25, 0, 0x18000
	v_add_u32_e32 v148, s25, v149
	s_add_i32 s28, 0, 0x1c000
	ds_read_b128 v[142:145], v148
	ds_read_b128 v[154:157], v148 offset:1024
	ds_read_b128 v[158:161], v148 offset:2048
	ds_read_b128 v[162:165], v148 offset:3072
	v_add_u32_e32 v148, s28, v149
	ds_read_b128 v[166:169], v148
	ds_read_b128 v[170:173], v148 offset:1024
	ds_read_b128 v[194:197], v148 offset:2048
	ds_read_b128 v[198:201], v148 offset:3072
	s_add_u32 s26, s26, 0x40000
	s_addc_u32 s27, s27, 0
	s_mov_b32 m0, s56
	v_lshl_add_u64 v[236:237], s[26:27], 0, v[134:135]
	ds_read_b128 v[202:205], v153 offset:32768
	ds_read_b128 v[206:209], v153 offset:33792
	ds_read_b128 v[210:213], v153 offset:34816
	ds_read_b128 v[214:217], v153 offset:35840
	ds_read_b128 v[218:221], v153 offset:36864
	ds_read_b128 v[222:225], v153 offset:37888
	ds_read_b128 v[226:229], v153 offset:38912
	ds_read_b128 v[230:233], v153 offset:39936
	global_load_lds_dwordx4 v[236:237], off
	v_lshl_add_u64 v[236:237], s[26:27], 0, v[130:131]
	s_mov_b32 m0, s57
	s_nop 0
	global_load_lds_dwordx4 v[236:237], off
	s_waitcnt vmcnt(8)
	s_waitcnt lgkmcnt(0)
	s_barrier
	s_waitcnt lgkmcnt(0)
	v_mfma_f32_16x16x32_bf16 v[124:127], v[142:145], v[202:205], v[124:127]
	v_mfma_f32_16x16x32_bf16 v[120:123], v[158:161], v[202:205], v[120:123]
	v_mfma_f32_16x16x32_bf16 v[108:111], v[142:145], v[210:213], v[108:111]
	v_mfma_f32_16x16x32_bf16 v[104:107], v[158:161], v[210:213], v[104:107]
	v_mfma_f32_16x16x32_bf16 v[92:95], v[142:145], v[218:221], v[92:95]
	v_mfma_f32_16x16x32_bf16 v[88:91], v[158:161], v[218:221], v[88:91]
	v_mfma_f32_16x16x32_bf16 v[76:79], v[142:145], v[226:229], v[76:79]
	v_mfma_f32_16x16x32_bf16 v[72:75], v[158:161], v[226:229], v[72:75]
	v_mfma_f32_16x16x32_bf16 v[124:127], v[154:157], v[206:209], v[124:127]
	v_mfma_f32_16x16x32_bf16 v[120:123], v[162:165], v[206:209], v[120:123]
	v_mfma_f32_16x16x32_bf16 v[108:111], v[154:157], v[214:217], v[108:111]
	v_mfma_f32_16x16x32_bf16 v[104:107], v[162:165], v[214:217], v[104:107]
	v_mfma_f32_16x16x32_bf16 v[92:95], v[154:157], v[222:225], v[92:95]
	v_mfma_f32_16x16x32_bf16 v[88:91], v[162:165], v[222:225], v[88:91]
	v_mfma_f32_16x16x32_bf16 v[76:79], v[154:157], v[230:233], v[76:79]
	v_mfma_f32_16x16x32_bf16 v[72:75], v[162:165], v[230:233], v[72:75]
	v_mfma_f32_16x16x32_bf16 v[116:119], v[166:169], v[202:205], v[116:119]
	v_mfma_f32_16x16x32_bf16 v[112:115], v[194:197], v[202:205], v[112:115]
	v_mfma_f32_16x16x32_bf16 v[100:103], v[166:169], v[210:213], v[100:103]
	v_mfma_f32_16x16x32_bf16 v[96:99], v[194:197], v[210:213], v[96:99]
	v_mfma_f32_16x16x32_bf16 v[84:87], v[166:169], v[218:221], v[84:87]
	v_mfma_f32_16x16x32_bf16 v[80:83], v[194:197], v[218:221], v[80:83]
	v_mfma_f32_16x16x32_bf16 v[68:71], v[166:169], v[226:229], v[68:71]
	v_mfma_f32_16x16x32_bf16 v[64:67], v[194:197], v[226:229], v[64:67]
	v_mfma_f32_16x16x32_bf16 v[116:119], v[170:173], v[206:209], v[116:119]
	v_mfma_f32_16x16x32_bf16 v[112:115], v[198:201], v[206:209], v[112:115]
	v_mfma_f32_16x16x32_bf16 v[100:103], v[170:173], v[214:217], v[100:103]
	v_mfma_f32_16x16x32_bf16 v[96:99], v[198:201], v[214:217], v[96:99]
	v_mfma_f32_16x16x32_bf16 v[84:87], v[170:173], v[222:225], v[84:87]
	v_mfma_f32_16x16x32_bf16 v[80:83], v[198:201], v[222:225], v[80:83]
	v_mfma_f32_16x16x32_bf16 v[68:71], v[170:173], v[230:233], v[68:71]
	v_mfma_f32_16x16x32_bf16 v[64:67], v[198:201], v[230:233], v[64:67]
	s_barrier
; #define PG8_STAGE(bufoff, gbase, voff) do { _Pragma("unroll") for (int _i = 0; _i < 2; ++_i) \
;         __builtin_amdgcn_global_load_lds((const unsigned*)((const char*)(gbase) + (voff)[_i]), (PG8_LAS unsigned*)(lds + (bufoff) + ldsw + _i * 8192), 16, 0, 0); } while (0)
; #define PG8_LDA(dst, b, h) do { _Pragma("unroll") for (int m = 0; m < 4; ++m) _Pragma("unroll") for (int k = 0; k < 2; ++k) dst[m][k] = *(const PG8_LAS bf16x8*)(lds + PG8_SA(b, h) + aoff + m * 2048 + k * 1024); } while (0)
; #define PG8_MMA(ai, bj, At, Bt) do { __builtin_amdgcn_s_setprio(1); _Pragma("unroll") for (int m = 0; m < 4; ++m) _Pragma("unroll") for (int n = 0; n < 2; ++n) _Pragma("unroll") for (int k = 0; k < 2; ++k) \
;         acc[ai][bj][m][n] = __builtin_amdgcn_mfma_f32_16x16x32_bf16(Bt[n][k], At[m][k], acc[ai][bj][m][n], 0, 0, 0); __builtin_amdgcn_s_setprio(0); } while (0)
; #define PG8_WAIT_V(n) asm volatile("s_waitcnt vmcnt(" #n ")" ::: "memory")
; #define PG8_WAIT_L(n) asm volatile("s_waitcnt lgkmcnt(" #n ")" ::: "memory")
; #define PG8_BAR __builtin_amdgcn_s_barrier()
; #define PG8_SCHED __builtin_amdgcn_sched_barrier(0)
; template <class Epi, class Sched, bool ALIGN_EPI = false, bool SP2 = false>
; __device__ __forceinline__ void gemm_phase(PG8_LAS unsigned char* lds, const Gemm g, const Sched& S, const Epi& E) {
;     ...
;             PG8_LDA(At, 1, 1); PG8_STAGE(PG8_SB(1, 0), b3, voffB); PG8_STAGE(PG8_SB(1, 1), b3 + hstep, voffB); PG8_STAGE(PG8_SA(1, 0), a3, voffA);
;             PG8_WAIT_V(8); PG8_WAIT_L(0); PG8_BAR; PG8_MMA(1, 0, At, B0); PG8_MMA(1, 1, At, B1); PG8_BAR; PG8_SCHED;
;     ...
;         if constexpr (ALIGN_EPI) { if (wr == 0) PG8_BAR; }
	s_add_i32 s25, s25, s2
	v_lshl_add_u64 v[146:147], v[146:147], 0, s[36:37]
	s_mov_b32 m0, s25
	ds_read_b128 v[202:205], v153 offset:49152
	ds_read_b128 v[206:209], v153 offset:50176
	ds_read_b128 v[210:213], v153 offset:51200
	ds_read_b128 v[214:217], v153 offset:52224
	ds_read_b128 v[218:221], v153 offset:53248
	ds_read_b128 v[222:225], v153 offset:54272
	ds_read_b128 v[226:229], v153 offset:55296
	ds_read_b128 v[230:233], v153 offset:56320
	global_load_lds_dwordx4 v[146:147], off
	s_add_i32 m0, s25, 0x2000
	s_add_u32 s16, s16, 0x40080
	v_lshl_add_u64 v[146:147], v[174:175], 0, s[36:37]
	s_addc_u32 s17, s17, 0
	s_add_i32 s25, s28, s2
	global_load_lds_dwordx4 v[146:147], off
	v_lshl_add_u64 v[146:147], s[16:17], 0, v[132:133]
	s_mov_b32 m0, s25
	s_nop 0
	global_load_lds_dwordx4 v[146:147], off
	v_lshl_add_u64 v[146:147], s[16:17], 0, v[128:129]
	s_add_i32 m0, s25, 0x2000
	s_nop 0
	global_load_lds_dwordx4 v[146:147], off
	v_lshl_add_u64 v[146:147], v[178:179], 0, s[36:37]
	s_mov_b32 m0, s59
	s_nop 0
	global_load_lds_dwordx4 v[146:147], off
	v_lshl_add_u64 v[146:147], v[234:235], 0, s[36:37]
	s_mov_b32 m0, s62
	s_nop 0
	global_load_lds_dwordx4 v[146:147], off
	s_waitcnt vmcnt(8)
	s_waitcnt lgkmcnt(0)
	s_barrier
	s_waitcnt lgkmcnt(0)
	v_mfma_f32_16x16x32_bf16 v[60:63], v[142:145], v[202:205], v[60:63]
	v_mfma_f32_16x16x32_bf16 v[56:59], v[158:161], v[202:205], v[56:59]
	v_mfma_f32_16x16x32_bf16 v[44:47], v[142:145], v[210:213], v[44:47]
	v_mfma_f32_16x16x32_bf16 v[40:43], v[158:161], v[210:213], v[40:43]
	v_mfma_f32_16x16x32_bf16 v[28:31], v[142:145], v[218:221], v[28:31]
	v_mfma_f32_16x16x32_bf16 v[24:27], v[158:161], v[218:221], v[24:27]
	v_mfma_f32_16x16x32_bf16 v[12:15], v[142:145], v[226:229], v[12:15]
	v_mfma_f32_16x16x32_bf16 v[8:11], v[158:161], v[226:229], v[8:11]
	v_mfma_f32_16x16x32_bf16 v[60:63], v[154:157], v[206:209], v[60:63]
	v_mfma_f32_16x16x32_bf16 v[56:59], v[162:165], v[206:209], v[56:59]
	v_mfma_f32_16x16x32_bf16 v[44:47], v[154:157], v[214:217], v[44:47]
	v_mfma_f32_16x16x32_bf16 v[40:43], v[162:165], v[214:217], v[40:43]
	v_mfma_f32_16x16x32_bf16 v[28:31], v[154:157], v[222:225], v[28:31]
	v_mfma_f32_16x16x32_bf16 v[24:27], v[162:165], v[222:225], v[24:27]
	v_mfma_f32_16x16x32_bf16 v[12:15], v[154:157], v[230:233], v[12:15]
	v_mfma_f32_16x16x32_bf16 v[8:11], v[162:165], v[230:233], v[8:11]
	v_mfma_f32_16x16x32_bf16 v[52:55], v[166:169], v[202:205], v[52:55]
	v_mfma_f32_16x16x32_bf16 v[48:51], v[194:197], v[202:205], v[48:51]
	v_mfma_f32_16x16x32_bf16 v[36:39], v[166:169], v[210:213], v[36:39]
	v_mfma_f32_16x16x32_bf16 v[32:35], v[194:197], v[210:213], v[32:35]
	v_mfma_f32_16x16x32_bf16 v[20:23], v[166:169], v[218:221], v[20:23]
	v_mfma_f32_16x16x32_bf16 v[16:19], v[194:197], v[218:221], v[16:19]
	v_mfma_f32_16x16x32_bf16 v[4:7], v[166:169], v[226:229], v[4:7]
	v_mfma_f32_16x16x32_bf16 v[0:3], v[194:197], v[226:229], v[0:3]
	v_mfma_f32_16x16x32_bf16 v[52:55], v[170:173], v[206:209], v[52:55]
	v_mfma_f32_16x16x32_bf16 v[48:51], v[198:201], v[206:209], v[48:51]
	v_mfma_f32_16x16x32_bf16 v[36:39], v[170:173], v[214:217], v[36:39]
	v_mfma_f32_16x16x32_bf16 v[32:35], v[198:201], v[214:217], v[32:35]
	v_mfma_f32_16x16x32_bf16 v[20:23], v[170:173], v[222:225], v[20:23]
	v_mfma_f32_16x16x32_bf16 v[16:19], v[198:201], v[222:225], v[16:19]
	v_mfma_f32_16x16x32_bf16 v[4:7], v[170:173], v[230:233], v[4:7]
	v_mfma_f32_16x16x32_bf16 v[0:3], v[198:201], v[230:233], v[0:3]
	s_barrier
	s_add_i32 s24, s24, 2
	s_add_u32 s22, s22, 0x100
	s_addc_u32 s23, s23, 0
	s_add_u32 s0, s0, 0x100
	s_addc_u32 s1, s1, 0
	s_cmp_gt_u32 s24, 13
	s_cbranch_scc0 .LBB0_265
	s_setprio 0
	s_and_b64 vcc, exec, s[44:45]
	s_cbranch_vccz .LBB0_268
	s_barrier

; #define PG8_STAGE(bufoff, gbase, voff) do { _Pragma("unroll") for (int _i = 0; _i < 2; ++_i) \
;         __builtin_amdgcn_global_load_lds((const unsigned*)((const char*)(gbase) + (voff)[_i]), (PG8_LAS unsigned*)(lds + (bufoff) + ldsw + _i * 8192), 16, 0, 0); } while (0)
; #define PG8_LDA(dst, b, h) do { _Pragma("unroll") for (int m = 0; m < 4; ++m) _Pragma("unroll") for (int k = 0; k < 2; ++k) dst[m][k] = *(const PG8_LAS bf16x8*)(lds + PG8_SA(b, h) + aoff + m * 2048 + k * 1024); } while (0)
; #define PG8_LDB(dst, b, h) do { _Pragma("unroll") for (int n = 0; n < 2; ++n) _Pragma("unroll") for (int k = 0; k < 2; ++k) dst[n][k] = *(const PG8_LAS bf16x8*)(lds + PG8_SB(b, h) + boff + n * 2048 + k * 1024); } while (0)
; #define PG8_WAIT_V(n) asm volatile("s_waitcnt vmcnt(" #n ")" ::: "memory")
; #define PG8_WAIT_L(n) asm volatile("s_waitcnt lgkmcnt(" #n ")" ::: "memory")
; #define PG8_BAR __builtin_amdgcn_s_barrier()
; #define PG8_SCHED __builtin_amdgcn_sched_barrier(0)
; template <class Epi, class Sched, bool ALIGN_EPI = false, bool SP2 = false>
; __device__ __forceinline__ void gemm_phase(PG8_LAS unsigned char* lds, const Gemm g, const Sched& S, const Epi& E) {
;     ...
;         const char* nA = has_next ? (const char*)g.A + (size_t)nxt.pm * tstep : cA; const char* nB = has_next ? (const char*)g.Bt + (size_t)nxt.pn * tstep : cB;
;         for (int t = 0; t < nt; t += 2) {
;             const bool last = (t == nt - 2);
;             const char* a1 = cA + (size_t)(t + 1) * kstep;
;             const char* a2 = last ? nA : cA + (size_t)(t + 2) * kstep; const char* b2 = last ? nB : cB + (size_t)(t + 2) * kstep;
;             const char* a3 = a2 + kstep; const char* b3 = b2 + kstep;
;             if (last && has_next) S.a_ready(nxt);
;             if constexpr (SP2) {
;             PG8_LDB(B0, 0, 0); PG8_LDB(B1, 0, 1); PG8_SCHED; PG8_LDA(At, 0, 0); PG8_STAGE(PG8_SA(1, 1), a1 + hstep, voffA);
;             PG8_WAIT_V(8); PG8_WAIT_L(0); PG8_BAR; PG8_MMA(0, 0, At, B0); PG8_MMA(0, 1, At, B1); PG8_BAR; PG8_SCHED;
;     ...
; #pragma unroll
;         for (int a = 0; a < 2; ++a)
; #pragma unroll
;             for (int b = 0; b < 2; ++b)
; #pragma unroll
;                 for (int m = 0; m < 4; ++m)
; #pragma unroll
;                     for (int n = 0; n < 2; ++n) acc[a][b][m][n] = (f32x4){0.f, 0.f, 0.f, 0.f};
.LBB0_557:
	s_ashr_i32 s43, s42, 31
	s_lshl_b64 s[34:35], s[42:43], 19
	s_add_u32 s44, s2, s34
	s_addc_u32 s45, s3, s35
	s_and_b64 s[34:35], s[4:5], exec
	s_cselect_b32 s33, s45, s51
	s_cselect_b32 s34, s44, s50
	s_ashr_i32 s41, s40, 31
	s_lshl_b64 s[46:47], s[40:41], 19
	s_add_u32 s46, s10, s46
	s_addc_u32 s47, s11, s47
	s_and_b64 s[52:53], s[4:5], exec
	s_cselect_b32 s35, s47, s49
	s_cselect_b32 s41, s46, s48
	s_add_u32 s43, s48, 0x100
	s_addc_u32 s54, s49, 0
	s_add_u32 s48, s50, 0x40080
	v_mov_b32_e32 v0, 0
	s_addc_u32 s49, s51, 0
	s_mov_b32 s55, -2
	s_waitcnt lgkmcnt(0)
	v_mov_b32_e32 v1, v0
	v_mov_b32_e32 v2, v0
	v_mov_b32_e32 v3, v0
	v_mov_b32_e32 v4, v0
	v_mov_b32_e32 v5, v0
	v_mov_b32_e32 v6, v0
	v_mov_b32_e32 v7, v0
	v_mov_b32_e32 v16, v0
	v_mov_b32_e32 v17, v0
	v_mov_b32_e32 v18, v0
	v_mov_b32_e32 v19, v0
	v_mov_b32_e32 v20, v0
	v_mov_b32_e32 v21, v0
	v_mov_b32_e32 v22, v0
	v_mov_b32_e32 v23, v0
	v_mov_b32_e32 v32, v0
	v_mov_b32_e32 v33, v0
	v_mov_b32_e32 v34, v0
	v_mov_b32_e32 v35, v0
	v_mov_b32_e32 v36, v0
	v_mov_b32_e32 v37, v0
	v_mov_b32_e32 v38, v0
	v_mov_b32_e32 v39, v0
	v_mov_b32_e32 v48, v0
	v_mov_b32_e32 v49, v0
	v_mov_b32_e32 v50, v0
	v_mov_b32_e32 v51, v0
	v_mov_b32_e32 v52, v0
	v_mov_b32_e32 v53, v0
	v_mov_b32_e32 v54, v0
	v_mov_b32_e32 v55, v0
	v_mov_b32_e32 v8, v0
	v_mov_b32_e32 v9, v0
	v_mov_b32_e32 v10, v0
	v_mov_b32_e32 v11, v0
	v_mov_b32_e32 v12, v0
	v_mov_b32_e32 v13, v0
	v_mov_b32_e32 v14, v0
	v_mov_b32_e32 v15, v0
	v_mov_b32_e32 v24, v0
	v_mov_b32_e32 v25, v0
	v_mov_b32_e32 v26, v0
	v_mov_b32_e32 v27, v0
	v_mov_b32_e32 v28, v0
	v_mov_b32_e32 v29, v0
	v_mov_b32_e32 v30, v0
	v_mov_b32_e32 v31, v0
	v_mov_b32_e32 v40, v0
	v_mov_b32_e32 v41, v0
	v_mov_b32_e32 v42, v0
	v_mov_b32_e32 v43, v0
	v_mov_b32_e32 v44, v0
	v_mov_b32_e32 v45, v0
	v_mov_b32_e32 v46, v0
	v_mov_b32_e32 v47, v0
	v_mov_b32_e32 v56, v0
	v_mov_b32_e32 v57, v0
	v_mov_b32_e32 v58, v0
	v_mov_b32_e32 v59, v0
	v_mov_b32_e32 v60, v0
	v_mov_b32_e32 v61, v0
	v_mov_b32_e32 v62, v0
	v_mov_b32_e32 v63, v0
	v_mov_b32_e32 v64, v0
	v_mov_b32_e32 v65, v0
	v_mov_b32_e32 v66, v0
	v_mov_b32_e32 v67, v0
	v_mov_b32_e32 v68, v0
	v_mov_b32_e32 v69, v0
	v_mov_b32_e32 v70, v0
	v_mov_b32_e32 v71, v0
	v_mov_b32_e32 v80, v0
	v_mov_b32_e32 v81, v0
	v_mov_b32_e32 v82, v0
	v_mov_b32_e32 v83, v0
	v_mov_b32_e32 v84, v0
	v_mov_b32_e32 v85, v0
	v_mov_b32_e32 v86, v0
	v_mov_b32_e32 v87, v0
	v_mov_b32_e32 v96, v0
	v_mov_b32_e32 v97, v0
	v_mov_b32_e32 v98, v0
	v_mov_b32_e32 v99, v0
	v_mov_b32_e32 v100, v0
	v_mov_b32_e32 v101, v0
	v_mov_b32_e32 v102, v0
	v_mov_b32_e32 v103, v0
	v_mov_b32_e32 v136, v0
	v_mov_b32_e32 v137, v0
	v_mov_b32_e32 v138, v0
	v_mov_b32_e32 v139, v0
	v_mov_b32_e32 v140, v0
	v_mov_b32_e32 v141, v0
	v_mov_b32_e32 v142, v0
	v_mov_b32_e32 v143, v0
	v_mov_b32_e32 v72, v0
	v_mov_b32_e32 v73, v0
	v_mov_b32_e32 v74, v0
	v_mov_b32_e32 v75, v0
	v_mov_b32_e32 v76, v0
	v_mov_b32_e32 v77, v0
	v_mov_b32_e32 v78, v0
	v_mov_b32_e32 v79, v0
	v_mov_b32_e32 v88, v0
	v_mov_b32_e32 v89, v0
	v_mov_b32_e32 v90, v0
	v_mov_b32_e32 v91, v0
	v_mov_b32_e32 v92, v0
	v_mov_b32_e32 v93, v0
	v_mov_b32_e32 v94, v0
	v_mov_b32_e32 v95, v0
	v_mov_b32_e32 v104, v0
	v_mov_b32_e32 v105, v0
	v_mov_b32_e32 v106, v0
	v_mov_b32_e32 v107, v0
	v_mov_b32_e32 v108, v0
	v_mov_b32_e32 v109, v0
	v_mov_b32_e32 v110, v0
	v_mov_b32_e32 v111, v0
	v_mov_b32_e32 v144, v0
	v_mov_b32_e32 v145, v0
	v_mov_b32_e32 v146, v0
	v_mov_b32_e32 v147, v0
	v_mov_b32_e32 v148, v0
	v_mov_b32_e32 v149, v0
	v_mov_b32_e32 v150, v0
	v_mov_b32_e32 v151, v0
	s_cmp_eq_u32 s101, 0
	s_cbranch_scc1 .Lsp_skip2
	s_setprio 1
.Lsp_skip2:
.LBB0_558:
	s_add_u32 s50, s48, 0xfffc0080
	s_addc_u32 s51, s49, -1
	s_add_i32 s56, 0, 0x10000
	s_cmp_eq_u32 s55, 12
	s_cselect_b32 s53, s33, s51
	s_cselect_b32 s52, s34, s50
	s_cselect_b32 s51, s35, s54
	s_cselect_b32 s50, s41, s43
	s_add_i32 s58, 0, 0x14000
	v_add_u32_e32 v124, s56, v201
	v_add_u32_e32 v168, s58, v201
	ds_read_b128 v[112:115], v124
	ds_read_b128 v[116:119], v124 offset:1024
	ds_read_b128 v[120:123], v124 offset:2048
	ds_read_b128 v[124:127], v124 offset:3072
	ds_read_b128 v[128:131], v168
	ds_read_b128 v[132:135], v168 offset:1024
	ds_read_b128 v[164:167], v168 offset:2048
	ds_read_b128 v[168:171], v168 offset:3072
	v_lshl_add_u64 v[178:179], s[48:49], 0, v[162:163]
	s_add_i32 m0, s21, 0xc000
	ds_read_b128 v[172:175], v203
	ds_read_b128 v[194:197], v203 offset:1024
	ds_read_b128 v[204:207], v203 offset:2048
	ds_read_b128 v[208:211], v203 offset:3072
	ds_read_b128 v[212:215], v203 offset:4096
	ds_read_b128 v[216:219], v203 offset:5120
	ds_read_b128 v[220:223], v203 offset:6144
	ds_read_b128 v[224:227], v203 offset:7168
	global_load_lds_dwordx4 v[178:179], off
	v_lshl_add_u64 v[178:179], s[48:49], 0, v[160:161]
	s_add_i32 m0, s21, 0xe000
	s_nop 0
	global_load_lds_dwordx4 v[178:179], off
	s_waitcnt vmcnt(8)
	s_waitcnt lgkmcnt(0)
	s_barrier
; #define PG8_STAGE(bufoff, gbase, voff) do { _Pragma("unroll") for (int _i = 0; _i < 2; ++_i) \
;         __builtin_amdgcn_global_load_lds((const unsigned*)((const char*)(gbase) + (voff)[_i]), (PG8_LAS unsigned*)(lds + (bufoff) + ldsw + _i * 8192), 16, 0, 0); } while (0)
; #define PG8_LDA(dst, b, h) do { _Pragma("unroll") for (int m = 0; m < 4; ++m) _Pragma("unroll") for (int k = 0; k < 2; ++k) dst[m][k] = *(const PG8_LAS bf16x8*)(lds + PG8_SA(b, h) + aoff + m * 2048 + k * 1024); } while (0)
; #define PG8_MMA(ai, bj, At, Bt) do { __builtin_amdgcn_s_setprio(1); _Pragma("unroll") for (int m = 0; m < 4; ++m) _Pragma("unroll") for (int n = 0; n < 2; ++n) _Pragma("unroll") for (int k = 0; k < 2; ++k) \
;         acc[ai][bj][m][n] = __builtin_amdgcn_mfma_f32_16x16x32_bf16(Bt[n][k], At[m][k], acc[ai][bj][m][n], 0, 0, 0); __builtin_amdgcn_s_setprio(0); } while (0)
; #define PG8_WAIT_V(n) asm volatile("s_waitcnt vmcnt(" #n ")" ::: "memory")
; #define PG8_WAIT_L(n) asm volatile("s_waitcnt lgkmcnt(" #n ")" ::: "memory")
; #define PG8_BAR __builtin_amdgcn_s_barrier()
; #define PG8_SCHED __builtin_amdgcn_sched_barrier(0)
; template <class Epi, class Sched, bool ALIGN_EPI = false, bool SP2 = false>
; __device__ __forceinline__ void gemm_phase(PG8_LAS unsigned char* lds, const Gemm g, const Sched& S, const Epi& E) {
;     ...
;             PG8_WAIT_V(8); PG8_WAIT_L(0); PG8_BAR; PG8_MMA(0, 0, At, B0); PG8_MMA(0, 1, At, B1); PG8_BAR; PG8_SCHED;
;             PG8_LDA(At, 0, 1); PG8_STAGE(PG8_SB(0, 0), b2, voffB); PG8_STAGE(PG8_SB(0, 1), b2 + hstep, voffB); PG8_STAGE(PG8_SA(0, 0), a2, voffA);
;             PG8_WAIT_V(8); PG8_WAIT_L(0); PG8_BAR; PG8_MMA(1, 0, At, B0); PG8_MMA(1, 1, At, B1); PG8_BAR; PG8_SCHED;
	s_waitcnt lgkmcnt(0)
	v_mfma_f32_16x16x32_bf16 v[148:151], v[112:115], v[172:175], v[148:151]
	v_mfma_f32_16x16x32_bf16 v[144:147], v[120:123], v[172:175], v[144:147]
	v_mfma_f32_16x16x32_bf16 v[108:111], v[112:115], v[204:207], v[108:111]
	v_mfma_f32_16x16x32_bf16 v[104:107], v[120:123], v[204:207], v[104:107]
	v_mfma_f32_16x16x32_bf16 v[92:95], v[112:115], v[212:215], v[92:95]
	v_mfma_f32_16x16x32_bf16 v[88:91], v[120:123], v[212:215], v[88:91]
	v_mfma_f32_16x16x32_bf16 v[76:79], v[112:115], v[220:223], v[76:79]
	v_mfma_f32_16x16x32_bf16 v[72:75], v[120:123], v[220:223], v[72:75]
	v_mfma_f32_16x16x32_bf16 v[148:151], v[116:119], v[194:197], v[148:151]
	v_mfma_f32_16x16x32_bf16 v[144:147], v[124:127], v[194:197], v[144:147]
	v_mfma_f32_16x16x32_bf16 v[108:111], v[116:119], v[208:211], v[108:111]
	v_mfma_f32_16x16x32_bf16 v[104:107], v[124:127], v[208:211], v[104:107]
	v_mfma_f32_16x16x32_bf16 v[92:95], v[116:119], v[216:219], v[92:95]
	v_mfma_f32_16x16x32_bf16 v[88:91], v[124:127], v[216:219], v[88:91]
	v_mfma_f32_16x16x32_bf16 v[76:79], v[116:119], v[224:227], v[76:79]
	v_mfma_f32_16x16x32_bf16 v[72:75], v[124:127], v[224:227], v[72:75]
	v_mfma_f32_16x16x32_bf16 v[140:143], v[128:131], v[172:175], v[140:143]
	v_mfma_f32_16x16x32_bf16 v[136:139], v[164:167], v[172:175], v[136:139]
	v_mfma_f32_16x16x32_bf16 v[100:103], v[128:131], v[204:207], v[100:103]
	v_mfma_f32_16x16x32_bf16 v[96:99], v[164:167], v[204:207], v[96:99]
	v_mfma_f32_16x16x32_bf16 v[84:87], v[128:131], v[212:215], v[84:87]
	v_mfma_f32_16x16x32_bf16 v[80:83], v[164:167], v[212:215], v[80:83]
	v_mfma_f32_16x16x32_bf16 v[68:71], v[128:131], v[220:223], v[68:71]
	v_mfma_f32_16x16x32_bf16 v[64:67], v[164:167], v[220:223], v[64:67]
	v_mfma_f32_16x16x32_bf16 v[140:143], v[132:135], v[194:197], v[140:143]
	v_mfma_f32_16x16x32_bf16 v[136:139], v[168:171], v[194:197], v[136:139]
	v_mfma_f32_16x16x32_bf16 v[100:103], v[132:135], v[208:211], v[100:103]
	v_mfma_f32_16x16x32_bf16 v[96:99], v[168:171], v[208:211], v[96:99]
	v_mfma_f32_16x16x32_bf16 v[84:87], v[132:135], v[216:219], v[84:87]
	v_mfma_f32_16x16x32_bf16 v[80:83], v[168:171], v[216:219], v[80:83]
	v_mfma_f32_16x16x32_bf16 v[68:71], v[132:135], v[224:227], v[68:71]
	v_mfma_f32_16x16x32_bf16 v[64:67], v[168:171], v[224:227], v[64:67]
	s_barrier
	s_add_i32 s56, s56, s20
	v_lshl_add_u64 v[178:179], s[50:51], 0, v[156:157]
	s_mov_b32 m0, s56
	ds_read_b128 v[172:175], v203 offset:16384
	ds_read_b128 v[194:197], v203 offset:17408
	ds_read_b128 v[204:207], v203 offset:18432
	ds_read_b128 v[208:211], v203 offset:19456
	ds_read_b128 v[212:215], v203 offset:20480
	ds_read_b128 v[216:219], v203 offset:21504
	ds_read_b128 v[220:223], v203 offset:22528
	ds_read_b128 v[224:227], v203 offset:23552
	global_load_lds_dwordx4 v[178:179], off
	s_add_i32 m0, s56, 0x2000
	s_add_u32 s56, s50, 0x40000
	v_lshl_add_u64 v[198:199], s[50:51], 0, v[152:153]
	s_addc_u32 s57, s51, 0
	s_add_i32 s58, s58, s20
	global_load_lds_dwordx4 v[198:199], off
	v_lshl_add_u64 v[228:229], s[56:57], 0, v[156:157]
	s_mov_b32 m0, s58
	v_lshl_add_u64 v[230:231], s[52:53], 0, v[154:155]
	global_load_lds_dwordx4 v[228:229], off
	v_lshl_add_u64 v[228:229], s[56:57], 0, v[152:153]
	s_add_i32 m0, s58, 0x2000
	s_nop 0
	global_load_lds_dwordx4 v[228:229], off
	v_lshl_add_u64 v[228:229], s[52:53], 0, v[158:159]
	s_mov_b32 m0, s21
	s_nop 0
	global_load_lds_dwordx4 v[228:229], off
	s_mov_b32 m0, s22
	s_nop 0
	global_load_lds_dwordx4 v[230:231], off
	s_waitcnt vmcnt(8)
	s_waitcnt lgkmcnt(0)
	s_barrier
	s_waitcnt lgkmcnt(0)
	v_mfma_f32_16x16x32_bf16 v[60:63], v[112:115], v[172:175], v[60:63]
	v_mfma_f32_16x16x32_bf16 v[56:59], v[120:123], v[172:175], v[56:59]
	v_mfma_f32_16x16x32_bf16 v[44:47], v[112:115], v[204:207], v[44:47]
	v_mfma_f32_16x16x32_bf16 v[40:43], v[120:123], v[204:207], v[40:43]
	v_mfma_f32_16x16x32_bf16 v[28:31], v[112:115], v[212:215], v[28:31]
	v_mfma_f32_16x16x32_bf16 v[24:27], v[120:123], v[212:215], v[24:27]
	v_mfma_f32_16x16x32_bf16 v[12:15], v[112:115], v[220:223], v[12:15]
	v_mfma_f32_16x16x32_bf16 v[8:11], v[120:123], v[220:223], v[8:11]
	v_mfma_f32_16x16x32_bf16 v[60:63], v[116:119], v[194:197], v[60:63]
	v_mfma_f32_16x16x32_bf16 v[56:59], v[124:127], v[194:197], v[56:59]
	v_mfma_f32_16x16x32_bf16 v[44:47], v[116:119], v[208:211], v[44:47]
	v_mfma_f32_16x16x32_bf16 v[40:43], v[124:127], v[208:211], v[40:43]
	v_mfma_f32_16x16x32_bf16 v[28:31], v[116:119], v[216:219], v[28:31]
	v_mfma_f32_16x16x32_bf16 v[24:27], v[124:127], v[216:219], v[24:27]
	v_mfma_f32_16x16x32_bf16 v[12:15], v[116:119], v[224:227], v[12:15]
	v_mfma_f32_16x16x32_bf16 v[8:11], v[124:127], v[224:227], v[8:11]
	v_mfma_f32_16x16x32_bf16 v[52:55], v[128:131], v[172:175], v[52:55]
	v_mfma_f32_16x16x32_bf16 v[48:51], v[164:167], v[172:175], v[48:51]
	v_mfma_f32_16x16x32_bf16 v[36:39], v[128:131], v[204:207], v[36:39]
	v_mfma_f32_16x16x32_bf16 v[32:35], v[164:167], v[204:207], v[32:35]
	v_mfma_f32_16x16x32_bf16 v[20:23], v[128:131], v[212:215], v[20:23]
	v_mfma_f32_16x16x32_bf16 v[16:19], v[164:167], v[212:215], v[16:19]
	v_mfma_f32_16x16x32_bf16 v[4:7], v[128:131], v[220:223], v[4:7]
	v_mfma_f32_16x16x32_bf16 v[0:3], v[164:167], v[220:223], v[0:3]
	v_mfma_f32_16x16x32_bf16 v[52:55], v[132:135], v[194:197], v[52:55]
	v_mfma_f32_16x16x32_bf16 v[48:51], v[168:171], v[194:197], v[48:51]
	v_mfma_f32_16x16x32_bf16 v[36:39], v[132:135], v[208:211], v[36:39]
	v_mfma_f32_16x16x32_bf16 v[32:35], v[168:171], v[208:211], v[32:35]
	v_mfma_f32_16x16x32_bf16 v[20:23], v[132:135], v[216:219], v[20:23]
	v_mfma_f32_16x16x32_bf16 v[16:19], v[168:171], v[216:219], v[16:19]
	v_mfma_f32_16x16x32_bf16 v[4:7], v[132:135], v[224:227], v[4:7]
	v_mfma_f32_16x16x32_bf16 v[0:3], v[168:171], v[224:227], v[0:3]
	s_barrier
; #define PG8_STAGE(bufoff, gbase, voff) do { _Pragma("unroll") for (int _i = 0; _i < 2; ++_i) \
;         __builtin_amdgcn_global_load_lds((const unsigned*)((const char*)(gbase) + (voff)[_i]), (PG8_LAS unsigned*)(lds + (bufoff) + ldsw + _i * 8192), 16, 0, 0); } while (0)
; #define PG8_LDA(dst, b, h) do { _Pragma("unroll") for (int m = 0; m < 4; ++m) _Pragma("unroll") for (int k = 0; k < 2; ++k) dst[m][k] = *(const PG8_LAS bf16x8*)(lds + PG8_SA(b, h) + aoff + m * 2048 + k * 1024); } while (0)
; #define PG8_LDB(dst, b, h) do { _Pragma("unroll") for (int n = 0; n < 2; ++n) _Pragma("unroll") for (int k = 0; k < 2; ++k) dst[n][k] = *(const PG8_LAS bf16x8*)(lds + PG8_SB(b, h) + boff + n * 2048 + k * 1024); } while (0)
; #define PG8_MMA(ai, bj, At, Bt) do { __builtin_amdgcn_s_setprio(1); _Pragma("unroll") for (int m = 0; m < 4; ++m) _Pragma("unroll") for (int n = 0; n < 2; ++n) _Pragma("unroll") for (int k = 0; k < 2; ++k) \
;         acc[ai][bj][m][n] = __builtin_amdgcn_mfma_f32_16x16x32_bf16(Bt[n][k], At[m][k], acc[ai][bj][m][n], 0, 0, 0); __builtin_amdgcn_s_setprio(0); } while (0)
; #define PG8_WAIT_V(n) asm volatile("s_waitcnt vmcnt(" #n ")" ::: "memory")
; #define PG8_WAIT_L(n) asm volatile("s_waitcnt lgkmcnt(" #n ")" ::: "memory")
; #define PG8_BAR __builtin_amdgcn_s_barrier()
; #define PG8_SCHED __builtin_amdgcn_sched_barrier(0)
; template <class Epi, class Sched, bool ALIGN_EPI = false, bool SP2 = false>
; __device__ __forceinline__ void gemm_phase(PG8_LAS unsigned char* lds, const Gemm g, const Sched& S, const Epi& E) {
;     ...
;             PG8_LDB(B0, 1, 0); PG8_LDB(B1, 1, 1); PG8_SCHED; PG8_LDA(At, 1, 0); PG8_STAGE(PG8_SA(0, 1), a2 + hstep, voffA);
;             PG8_WAIT_V(8); PG8_WAIT_L(0); PG8_BAR; PG8_MMA(0, 0, At, B0); PG8_MMA(0, 1, At, B1); PG8_BAR; PG8_SCHED;
	s_add_i32 s56, 0, 0x18000
	s_add_i32 s57, 0, 0x1c000
	v_add_u32_e32 v124, s56, v201
	v_add_u32_e32 v168, s57, v201
	ds_read_b128 v[112:115], v124
	ds_read_b128 v[116:119], v124 offset:1024
	ds_read_b128 v[120:123], v124 offset:2048
	ds_read_b128 v[124:127], v124 offset:3072
	ds_read_b128 v[128:131], v168
	ds_read_b128 v[132:135], v168 offset:1024
	ds_read_b128 v[164:167], v168 offset:2048
	ds_read_b128 v[168:171], v168 offset:3072
	s_add_u32 s52, s52, 0x40000
	s_addc_u32 s53, s53, 0
	s_mov_b32 m0, s23
	v_lshl_add_u64 v[232:233], s[52:53], 0, v[158:159]
	ds_read_b128 v[172:175], v203 offset:32768
	ds_read_b128 v[194:197], v203 offset:33792
	ds_read_b128 v[204:207], v203 offset:34816
	ds_read_b128 v[208:211], v203 offset:35840
	ds_read_b128 v[212:215], v203 offset:36864
	ds_read_b128 v[216:219], v203 offset:37888
	ds_read_b128 v[220:223], v203 offset:38912
	ds_read_b128 v[224:227], v203 offset:39936
	global_load_lds_dwordx4 v[232:233], off
	v_lshl_add_u64 v[232:233], s[52:53], 0, v[154:155]
	s_mov_b32 m0, s24
	s_nop 0
	global_load_lds_dwordx4 v[232:233], off
	s_waitcnt vmcnt(8)
	s_waitcnt lgkmcnt(0)
	s_barrier
	s_waitcnt lgkmcnt(0)
	v_mfma_f32_16x16x32_bf16 v[148:151], v[112:115], v[172:175], v[148:151]
	v_mfma_f32_16x16x32_bf16 v[144:147], v[120:123], v[172:175], v[144:147]
	v_mfma_f32_16x16x32_bf16 v[108:111], v[112:115], v[204:207], v[108:111]
	v_mfma_f32_16x16x32_bf16 v[104:107], v[120:123], v[204:207], v[104:107]
	v_mfma_f32_16x16x32_bf16 v[92:95], v[112:115], v[212:215], v[92:95]
	v_mfma_f32_16x16x32_bf16 v[88:91], v[120:123], v[212:215], v[88:91]
	v_mfma_f32_16x16x32_bf16 v[76:79], v[112:115], v[220:223], v[76:79]
	v_mfma_f32_16x16x32_bf16 v[72:75], v[120:123], v[220:223], v[72:75]
	v_mfma_f32_16x16x32_bf16 v[148:151], v[116:119], v[194:197], v[148:151]
	v_mfma_f32_16x16x32_bf16 v[144:147], v[124:127], v[194:197], v[144:147]
	v_mfma_f32_16x16x32_bf16 v[108:111], v[116:119], v[208:211], v[108:111]
	v_mfma_f32_16x16x32_bf16 v[104:107], v[124:127], v[208:211], v[104:107]
	v_mfma_f32_16x16x32_bf16 v[92:95], v[116:119], v[216:219], v[92:95]
	v_mfma_f32_16x16x32_bf16 v[88:91], v[124:127], v[216:219], v[88:91]
	v_mfma_f32_16x16x32_bf16 v[76:79], v[116:119], v[224:227], v[76:79]
	v_mfma_f32_16x16x32_bf16 v[72:75], v[124:127], v[224:227], v[72:75]
	v_mfma_f32_16x16x32_bf16 v[140:143], v[128:131], v[172:175], v[140:143]
	v_mfma_f32_16x16x32_bf16 v[136:139], v[164:167], v[172:175], v[136:139]
	v_mfma_f32_16x16x32_bf16 v[100:103], v[128:131], v[204:207], v[100:103]
	v_mfma_f32_16x16x32_bf16 v[96:99], v[164:167], v[204:207], v[96:99]
	v_mfma_f32_16x16x32_bf16 v[84:87], v[128:131], v[212:215], v[84:87]
	v_mfma_f32_16x16x32_bf16 v[80:83], v[164:167], v[212:215], v[80:83]
	v_mfma_f32_16x16x32_bf16 v[68:71], v[128:131], v[220:223], v[68:71]
	v_mfma_f32_16x16x32_bf16 v[64:67], v[164:167], v[220:223], v[64:67]
	v_mfma_f32_16x16x32_bf16 v[140:143], v[132:135], v[194:197], v[140:143]
	v_mfma_f32_16x16x32_bf16 v[136:139], v[168:171], v[194:197], v[136:139]
	v_mfma_f32_16x16x32_bf16 v[100:103], v[132:135], v[208:211], v[100:103]
	v_mfma_f32_16x16x32_bf16 v[96:99], v[168:171], v[208:211], v[96:99]
	v_mfma_f32_16x16x32_bf16 v[84:87], v[132:135], v[216:219], v[84:87]
	v_mfma_f32_16x16x32_bf16 v[80:83], v[168:171], v[216:219], v[80:83]
	v_mfma_f32_16x16x32_bf16 v[68:71], v[132:135], v[224:227], v[68:71]
	v_mfma_f32_16x16x32_bf16 v[64:67], v[168:171], v[224:227], v[64:67]
	s_barrier
; #define PG8_STAGE(bufoff, gbase, voff) do { _Pragma("unroll") for (int _i = 0; _i < 2; ++_i) \
;         __builtin_amdgcn_global_load_lds((const unsigned*)((const char*)(gbase) + (voff)[_i]), (PG8_LAS unsigned*)(lds + (bufoff) + ldsw + _i * 8192), 16, 0, 0); } while (0)
; #define PG8_LDA(dst, b, h) do { _Pragma("unroll") for (int m = 0; m < 4; ++m) _Pragma("unroll") for (int k = 0; k < 2; ++k) dst[m][k] = *(const PG8_LAS bf16x8*)(lds + PG8_SA(b, h) + aoff + m * 2048 + k * 1024); } while (0)
; #define PG8_MMA(ai, bj, At, Bt) do { __builtin_amdgcn_s_setprio(1); _Pragma("unroll") for (int m = 0; m < 4; ++m) _Pragma("unroll") for (int n = 0; n < 2; ++n) _Pragma("unroll") for (int k = 0; k < 2; ++k) \
;         acc[ai][bj][m][n] = __builtin_amdgcn_mfma_f32_16x16x32_bf16(Bt[n][k], At[m][k], acc[ai][bj][m][n], 0, 0, 0); __builtin_amdgcn_s_setprio(0); } while (0)
; #define PG8_WAIT_V(n) asm volatile("s_waitcnt vmcnt(" #n ")" ::: "memory")
; #define PG8_WAIT_L(n) asm volatile("s_waitcnt lgkmcnt(" #n ")" ::: "memory")
; #define PG8_BAR __builtin_amdgcn_s_barrier()
; #define PG8_SCHED __builtin_amdgcn_sched_barrier(0)
; template <class Epi, class Sched, bool ALIGN_EPI = false, bool SP2 = false>
; __device__ __forceinline__ void gemm_phase(PG8_LAS unsigned char* lds, const Gemm g, const Sched& S, const Epi& E) {
;     ...
;             PG8_LDA(At, 1, 1); PG8_STAGE(PG8_SB(1, 0), b3, voffB); PG8_STAGE(PG8_SB(1, 1), b3 + hstep, voffB); PG8_STAGE(PG8_SA(1, 0), a3, voffA);
;             PG8_WAIT_V(8); PG8_WAIT_L(0); PG8_BAR; PG8_MMA(1, 0, At, B0); PG8_MMA(1, 1, At, B1); PG8_BAR; PG8_SCHED;
;     ...
;         if constexpr (ALIGN_EPI) { if (wr == 0) PG8_BAR; }
	s_add_i32 s52, s56, s20
	v_lshl_add_u64 v[178:179], v[178:179], 0, s[36:37]
	s_mov_b32 m0, s52
	ds_read_b128 v[172:175], v203 offset:49152
	ds_read_b128 v[194:197], v203 offset:50176
	ds_read_b128 v[204:207], v203 offset:51200
	ds_read_b128 v[208:211], v203 offset:52224
	ds_read_b128 v[212:215], v203 offset:53248
	ds_read_b128 v[216:219], v203 offset:54272
	ds_read_b128 v[220:223], v203 offset:55296
	ds_read_b128 v[224:227], v203 offset:56320
	global_load_lds_dwordx4 v[178:179], off
	s_add_i32 m0, s52, 0x2000
	s_add_u32 s50, s50, 0x40080
	v_lshl_add_u64 v[178:179], v[198:199], 0, s[36:37]
	s_addc_u32 s51, s51, 0
	s_add_i32 s52, s57, s20
	global_load_lds_dwordx4 v[178:179], off
	v_lshl_add_u64 v[178:179], s[50:51], 0, v[156:157]
	s_mov_b32 m0, s52
	s_nop 0
	global_load_lds_dwordx4 v[178:179], off
	v_lshl_add_u64 v[178:179], s[50:51], 0, v[152:153]
	s_add_i32 m0, s52, 0x2000
	s_nop 0
	global_load_lds_dwordx4 v[178:179], off
	v_lshl_add_u64 v[178:179], v[228:229], 0, s[36:37]
	s_mov_b32 m0, s28
	s_nop 0
	global_load_lds_dwordx4 v[178:179], off
	v_lshl_add_u64 v[178:179], v[230:231], 0, s[36:37]
	s_mov_b32 m0, s29
	s_nop 0
	global_load_lds_dwordx4 v[178:179], off
	s_waitcnt vmcnt(8)
	s_waitcnt lgkmcnt(0)
	s_barrier
	s_waitcnt lgkmcnt(0)
	v_mfma_f32_16x16x32_bf16 v[60:63], v[112:115], v[172:175], v[60:63]
	v_mfma_f32_16x16x32_bf16 v[56:59], v[120:123], v[172:175], v[56:59]
	v_mfma_f32_16x16x32_bf16 v[44:47], v[112:115], v[204:207], v[44:47]
	v_mfma_f32_16x16x32_bf16 v[40:43], v[120:123], v[204:207], v[40:43]
	v_mfma_f32_16x16x32_bf16 v[28:31], v[112:115], v[212:215], v[28:31]
	v_mfma_f32_16x16x32_bf16 v[24:27], v[120:123], v[212:215], v[24:27]
	v_mfma_f32_16x16x32_bf16 v[12:15], v[112:115], v[220:223], v[12:15]
	v_mfma_f32_16x16x32_bf16 v[8:11], v[120:123], v[220:223], v[8:11]
	v_mfma_f32_16x16x32_bf16 v[60:63], v[116:119], v[194:197], v[60:63]
	v_mfma_f32_16x16x32_bf16 v[56:59], v[124:127], v[194:197], v[56:59]
	v_mfma_f32_16x16x32_bf16 v[44:47], v[116:119], v[208:211], v[44:47]
	v_mfma_f32_16x16x32_bf16 v[40:43], v[124:127], v[208:211], v[40:43]
	v_mfma_f32_16x16x32_bf16 v[28:31], v[116:119], v[216:219], v[28:31]
	v_mfma_f32_16x16x32_bf16 v[24:27], v[124:127], v[216:219], v[24:27]
	v_mfma_f32_16x16x32_bf16 v[12:15], v[116:119], v[224:227], v[12:15]
	v_mfma_f32_16x16x32_bf16 v[8:11], v[124:127], v[224:227], v[8:11]
	v_mfma_f32_16x16x32_bf16 v[52:55], v[128:131], v[172:175], v[52:55]
	v_mfma_f32_16x16x32_bf16 v[48:51], v[164:167], v[172:175], v[48:51]
	v_mfma_f32_16x16x32_bf16 v[36:39], v[128:131], v[204:207], v[36:39]
	v_mfma_f32_16x16x32_bf16 v[32:35], v[164:167], v[204:207], v[32:35]
	v_mfma_f32_16x16x32_bf16 v[20:23], v[128:131], v[212:215], v[20:23]
	v_mfma_f32_16x16x32_bf16 v[16:19], v[164:167], v[212:215], v[16:19]
	v_mfma_f32_16x16x32_bf16 v[4:7], v[128:131], v[220:223], v[4:7]
	v_mfma_f32_16x16x32_bf16 v[0:3], v[164:167], v[220:223], v[0:3]
	v_mfma_f32_16x16x32_bf16 v[52:55], v[132:135], v[194:197], v[52:55]
	v_mfma_f32_16x16x32_bf16 v[48:51], v[168:171], v[194:197], v[48:51]
	v_mfma_f32_16x16x32_bf16 v[36:39], v[132:135], v[208:211], v[36:39]
	v_mfma_f32_16x16x32_bf16 v[32:35], v[168:171], v[208:211], v[32:35]
	v_mfma_f32_16x16x32_bf16 v[20:23], v[132:135], v[216:219], v[20:23]
	v_mfma_f32_16x16x32_bf16 v[16:19], v[168:171], v[216:219], v[16:19]
	v_mfma_f32_16x16x32_bf16 v[4:7], v[132:135], v[224:227], v[4:7]
	v_mfma_f32_16x16x32_bf16 v[0:3], v[168:171], v[224:227], v[0:3]
	s_barrier
	s_add_i32 s55, s55, 2
	s_add_u32 s43, s43, 0x100
	s_addc_u32 s54, s54, 0
	s_add_u32 s48, s48, 0x100
	s_addc_u32 s49, s49, 0
	s_cmp_gt_u32 s55, 13
	s_cbranch_scc0 .LBB0_558
	s_setprio 0
	s_and_b64 vcc, exec, s[26:27]
	s_cbranch_vccz .LBB0_561
	s_barrier

; #define PG8_STAGE(bufoff, gbase, voff) do { _Pragma("unroll") for (int _i = 0; _i < 2; ++_i) \
;         __builtin_amdgcn_global_load_lds((const unsigned*)((const char*)(gbase) + (voff)[_i]), (PG8_LAS unsigned*)(lds + (bufoff) + ldsw + _i * 8192), 16, 0, 0); } while (0)
; #define PG8_LDA(dst, b, h) do { _Pragma("unroll") for (int m = 0; m < 4; ++m) _Pragma("unroll") for (int k = 0; k < 2; ++k) dst[m][k] = *(const PG8_LAS bf16x8*)(lds + PG8_SA(b, h) + aoff + m * 2048 + k * 1024); } while (0)
; #define PG8_LDB(dst, b, h) do { _Pragma("unroll") for (int n = 0; n < 2; ++n) _Pragma("unroll") for (int k = 0; k < 2; ++k) dst[n][k] = *(const PG8_LAS bf16x8*)(lds + PG8_SB(b, h) + boff + n * 2048 + k * 1024); } while (0)
; #define PG8_WAIT_V(n) asm volatile("s_waitcnt vmcnt(" #n ")" ::: "memory")
; #define PG8_WAIT_L(n) asm volatile("s_waitcnt lgkmcnt(" #n ")" ::: "memory")
; #define PG8_BAR __builtin_amdgcn_s_barrier()
; #define PG8_SCHED __builtin_amdgcn_sched_barrier(0)
; template <class Epi, class Sched, bool ALIGN_EPI = false, bool SP2 = false>
; __device__ __forceinline__ void gemm_phase(PG8_LAS unsigned char* lds, const Gemm g, const Sched& S, const Epi& E) {
;     ...
;         const char* nA = has_next ? (const char*)g.A + (size_t)nxt.pm * tstep : cA; const char* nB = has_next ? (const char*)g.Bt + (size_t)nxt.pn * tstep : cB;
;         for (int t = 0; t < nt; t += 2) {
;             const bool last = (t == nt - 2);
;             const char* a1 = cA + (size_t)(t + 1) * kstep;
;             const char* a2 = last ? nA : cA + (size_t)(t + 2) * kstep; const char* b2 = last ? nB : cB + (size_t)(t + 2) * kstep;
;             const char* a3 = a2 + kstep; const char* b3 = b2 + kstep;
;             if (last && has_next) S.a_ready(nxt);
;             if constexpr (SP2) {
;             PG8_LDB(B0, 0, 0); PG8_LDB(B1, 0, 1); PG8_SCHED; PG8_LDA(At, 0, 0); PG8_STAGE(PG8_SA(1, 1), a1 + hstep, voffA);
;             PG8_WAIT_V(8); PG8_WAIT_L(0); PG8_BAR; PG8_MMA(0, 0, At, B0); PG8_MMA(0, 1, At, B1); PG8_BAR; PG8_SCHED;
;     ...
; #pragma unroll
;         for (int a = 0; a < 2; ++a)
; #pragma unroll
;             for (int b = 0; b < 2; ++b)
; #pragma unroll
;                 for (int m = 0; m < 4; ++m)
; #pragma unroll
;                     for (int n = 0; n < 2; ++n) acc[a][b][m][n] = (f32x4){0.f, 0.f, 0.f, 0.f};
.LBB0_658:
	s_ashr_i32 s41, s40, 31
	s_lshl_b64 s[34:35], s[40:41], 19
	s_add_u32 s42, s2, s34
	s_addc_u32 s43, s3, s35
	s_and_b64 s[34:35], s[0:1], exec
	s_cselect_b32 s33, s43, s49
	s_cselect_b32 s34, s42, s48
	s_ashr_i32 s27, s26, 31
	s_lshl_b64 s[44:45], s[26:27], 19
	s_add_u32 s44, s10, s44
	s_addc_u32 s45, s11, s45
	s_and_b64 s[50:51], s[0:1], exec
	s_cselect_b32 s27, s45, s47
	s_cselect_b32 s35, s44, s46
	s_add_u32 s41, s46, 0x100
	s_addc_u32 s52, s47, 0
	s_add_u32 s46, s48, 0x40080
	v_mov_b32_e32 v0, 0
	s_addc_u32 s47, s49, 0
	s_mov_b32 s53, -2
	v_mov_b32_e32 v1, v0
	v_mov_b32_e32 v2, v0
	v_mov_b32_e32 v3, v0
	v_mov_b32_e32 v4, v0
	v_mov_b32_e32 v5, v0
	v_mov_b32_e32 v6, v0
	v_mov_b32_e32 v7, v0
	v_mov_b32_e32 v16, v0
	v_mov_b32_e32 v17, v0
	v_mov_b32_e32 v18, v0
	v_mov_b32_e32 v19, v0
	v_mov_b32_e32 v20, v0
	v_mov_b32_e32 v21, v0
	v_mov_b32_e32 v22, v0
	v_mov_b32_e32 v23, v0
	v_mov_b32_e32 v32, v0
	v_mov_b32_e32 v33, v0
	v_mov_b32_e32 v34, v0
	v_mov_b32_e32 v35, v0
	v_mov_b32_e32 v36, v0
	v_mov_b32_e32 v37, v0
	v_mov_b32_e32 v38, v0
	v_mov_b32_e32 v39, v0
	v_mov_b32_e32 v48, v0
	v_mov_b32_e32 v49, v0
	v_mov_b32_e32 v50, v0
	v_mov_b32_e32 v51, v0
	v_mov_b32_e32 v52, v0
	v_mov_b32_e32 v53, v0
	v_mov_b32_e32 v54, v0
	v_mov_b32_e32 v55, v0
	v_mov_b32_e32 v8, v0
	v_mov_b32_e32 v9, v0
	v_mov_b32_e32 v10, v0
	v_mov_b32_e32 v11, v0
	v_mov_b32_e32 v12, v0
	v_mov_b32_e32 v13, v0
	v_mov_b32_e32 v14, v0
	v_mov_b32_e32 v15, v0
	v_mov_b32_e32 v24, v0
	v_mov_b32_e32 v25, v0
	v_mov_b32_e32 v26, v0
	v_mov_b32_e32 v27, v0
	v_mov_b32_e32 v28, v0
	v_mov_b32_e32 v29, v0
	v_mov_b32_e32 v30, v0
	v_mov_b32_e32 v31, v0
	v_mov_b32_e32 v40, v0
	v_mov_b32_e32 v41, v0
	v_mov_b32_e32 v42, v0
	v_mov_b32_e32 v43, v0
	v_mov_b32_e32 v44, v0
	v_mov_b32_e32 v45, v0
	v_mov_b32_e32 v46, v0
	v_mov_b32_e32 v47, v0
	v_mov_b32_e32 v56, v0
	v_mov_b32_e32 v57, v0
	v_mov_b32_e32 v58, v0
	v_mov_b32_e32 v59, v0
	v_mov_b32_e32 v60, v0
	v_mov_b32_e32 v61, v0
	v_mov_b32_e32 v62, v0
	v_mov_b32_e32 v63, v0
	v_mov_b32_e32 v64, v0
	v_mov_b32_e32 v65, v0
	v_mov_b32_e32 v66, v0
	v_mov_b32_e32 v67, v0
	v_mov_b32_e32 v68, v0
	v_mov_b32_e32 v69, v0
	v_mov_b32_e32 v70, v0
	v_mov_b32_e32 v71, v0
	v_mov_b32_e32 v80, v0
	v_mov_b32_e32 v81, v0
	v_mov_b32_e32 v82, v0
	v_mov_b32_e32 v83, v0
	v_mov_b32_e32 v84, v0
	v_mov_b32_e32 v85, v0
	v_mov_b32_e32 v86, v0
	v_mov_b32_e32 v87, v0
	v_mov_b32_e32 v96, v0
	v_mov_b32_e32 v97, v0
	v_mov_b32_e32 v98, v0
	v_mov_b32_e32 v99, v0
	v_mov_b32_e32 v100, v0
	v_mov_b32_e32 v101, v0
	v_mov_b32_e32 v102, v0
	v_mov_b32_e32 v103, v0
	v_mov_b32_e32 v112, v0
	v_mov_b32_e32 v113, v0
	v_mov_b32_e32 v114, v0
	v_mov_b32_e32 v115, v0
	v_mov_b32_e32 v116, v0
	v_mov_b32_e32 v117, v0
	v_mov_b32_e32 v118, v0
	v_mov_b32_e32 v119, v0
	v_mov_b32_e32 v72, v0
	v_mov_b32_e32 v73, v0
	v_mov_b32_e32 v74, v0
	v_mov_b32_e32 v75, v0
	v_mov_b32_e32 v76, v0
	v_mov_b32_e32 v77, v0
	v_mov_b32_e32 v78, v0
	v_mov_b32_e32 v79, v0
	v_mov_b32_e32 v88, v0
	v_mov_b32_e32 v89, v0
	v_mov_b32_e32 v90, v0
	v_mov_b32_e32 v91, v0
	v_mov_b32_e32 v92, v0
	v_mov_b32_e32 v93, v0
	v_mov_b32_e32 v94, v0
	v_mov_b32_e32 v95, v0
	v_mov_b32_e32 v104, v0
	v_mov_b32_e32 v105, v0
	v_mov_b32_e32 v106, v0
	v_mov_b32_e32 v107, v0
	v_mov_b32_e32 v108, v0
	v_mov_b32_e32 v109, v0
	v_mov_b32_e32 v110, v0
	v_mov_b32_e32 v111, v0
	v_mov_b32_e32 v120, v0
	v_mov_b32_e32 v121, v0
	v_mov_b32_e32 v122, v0
	v_mov_b32_e32 v123, v0
	v_mov_b32_e32 v124, v0
	v_mov_b32_e32 v125, v0
	v_mov_b32_e32 v126, v0
	v_mov_b32_e32 v127, v0
	s_cmp_eq_u32 s101, 0
	s_cbranch_scc1 .Lsp_skip3
	s_setprio 1
.Lsp_skip3:
.LBB0_659:
	s_add_u32 s48, s46, 0xfffc0080
	s_addc_u32 s49, s47, -1
	s_add_i32 s54, 0, 0x10000
	s_cmp_eq_u32 s53, 12
	s_cselect_b32 s51, s33, s49
	s_cselect_b32 s50, s34, s48
	v_add_u32_e32 v141, s54, v148
	s_cselect_b32 s49, s27, s52
	s_cselect_b32 s48, s35, s41
	s_add_i32 s56, 0, 0x14000
	ds_read_b128 v[142:145], v141
	ds_read_b128 v[152:155], v141 offset:1024
	ds_read_b128 v[156:159], v141 offset:2048
	ds_read_b128 v[160:163], v141 offset:3072
	v_add_u32_e32 v141, s56, v148
	ds_read_b128 v[164:167], v141
	ds_read_b128 v[168:171], v141 offset:1024
	ds_read_b128 v[172:175], v141 offset:2048
	ds_read_b128 v[194:197], v141 offset:3072
	v_lshl_add_u64 v[178:179], s[46:47], 0, v[138:139]
	s_add_i32 m0, s21, 0xc000
	ds_read_b128 v[198:201], v151
	ds_read_b128 v[202:205], v151 offset:1024
	ds_read_b128 v[206:209], v151 offset:2048
	ds_read_b128 v[210:213], v151 offset:3072
	ds_read_b128 v[214:217], v151 offset:4096
	ds_read_b128 v[218:221], v151 offset:5120
	ds_read_b128 v[222:225], v151 offset:6144
	ds_read_b128 v[226:229], v151 offset:7168
	global_load_lds_dwordx4 v[178:179], off
	v_lshl_add_u64 v[178:179], s[46:47], 0, v[136:137]
	s_add_i32 m0, s21, 0xe000
	s_nop 0
	global_load_lds_dwordx4 v[178:179], off
	s_waitcnt vmcnt(8)
	s_waitcnt lgkmcnt(0)
	s_barrier
; #define PG8_STAGE(bufoff, gbase, voff) do { _Pragma("unroll") for (int _i = 0; _i < 2; ++_i) \
;         __builtin_amdgcn_global_load_lds((const unsigned*)((const char*)(gbase) + (voff)[_i]), (PG8_LAS unsigned*)(lds + (bufoff) + ldsw + _i * 8192), 16, 0, 0); } while (0)
; #define PG8_LDA(dst, b, h) do { _Pragma("unroll") for (int m = 0; m < 4; ++m) _Pragma("unroll") for (int k = 0; k < 2; ++k) dst[m][k] = *(const PG8_LAS bf16x8*)(lds + PG8_SA(b, h) + aoff + m * 2048 + k * 1024); } while (0)
; #define PG8_MMA(ai, bj, At, Bt) do { __builtin_amdgcn_s_setprio(1); _Pragma("unroll") for (int m = 0; m < 4; ++m) _Pragma("unroll") for (int n = 0; n < 2; ++n) _Pragma("unroll") for (int k = 0; k < 2; ++k) \
;         acc[ai][bj][m][n] = __builtin_amdgcn_mfma_f32_16x16x32_bf16(Bt[n][k], At[m][k], acc[ai][bj][m][n], 0, 0, 0); __builtin_amdgcn_s_setprio(0); } while (0)
; #define PG8_WAIT_V(n) asm volatile("s_waitcnt vmcnt(" #n ")" ::: "memory")
; #define PG8_WAIT_L(n) asm volatile("s_waitcnt lgkmcnt(" #n ")" ::: "memory")
; #define PG8_BAR __builtin_amdgcn_s_barrier()
; #define PG8_SCHED __builtin_amdgcn_sched_barrier(0)
; template <class Epi, class Sched, bool ALIGN_EPI = false, bool SP2 = false>
; __device__ __forceinline__ void gemm_phase(PG8_LAS unsigned char* lds, const Gemm g, const Sched& S, const Epi& E) {
;     ...
;             PG8_WAIT_V(8); PG8_WAIT_L(0); PG8_BAR; PG8_MMA(0, 0, At, B0); PG8_MMA(0, 1, At, B1); PG8_BAR; PG8_SCHED;
;             PG8_LDA(At, 0, 1); PG8_STAGE(PG8_SB(0, 0), b2, voffB); PG8_STAGE(PG8_SB(0, 1), b2 + hstep, voffB); PG8_STAGE(PG8_SA(0, 0), a2, voffA);
;             PG8_WAIT_V(8); PG8_WAIT_L(0); PG8_BAR; PG8_MMA(1, 0, At, B0); PG8_MMA(1, 1, At, B1); PG8_BAR; PG8_SCHED;
	s_waitcnt lgkmcnt(0)
	v_mfma_f32_16x16x32_bf16 v[124:127], v[142:145], v[198:201], v[124:127]
	v_mfma_f32_16x16x32_bf16 v[120:123], v[156:159], v[198:201], v[120:123]
	v_mfma_f32_16x16x32_bf16 v[108:111], v[142:145], v[206:209], v[108:111]
	v_mfma_f32_16x16x32_bf16 v[104:107], v[156:159], v[206:209], v[104:107]
	v_mfma_f32_16x16x32_bf16 v[92:95], v[142:145], v[214:217], v[92:95]
	v_mfma_f32_16x16x32_bf16 v[88:91], v[156:159], v[214:217], v[88:91]
	v_mfma_f32_16x16x32_bf16 v[76:79], v[142:145], v[222:225], v[76:79]
	v_mfma_f32_16x16x32_bf16 v[72:75], v[156:159], v[222:225], v[72:75]
	v_mfma_f32_16x16x32_bf16 v[124:127], v[152:155], v[202:205], v[124:127]
	v_mfma_f32_16x16x32_bf16 v[120:123], v[160:163], v[202:205], v[120:123]
	v_mfma_f32_16x16x32_bf16 v[108:111], v[152:155], v[210:213], v[108:111]
	v_mfma_f32_16x16x32_bf16 v[104:107], v[160:163], v[210:213], v[104:107]
	v_mfma_f32_16x16x32_bf16 v[92:95], v[152:155], v[218:221], v[92:95]
	v_mfma_f32_16x16x32_bf16 v[88:91], v[160:163], v[218:221], v[88:91]
	v_mfma_f32_16x16x32_bf16 v[76:79], v[152:155], v[226:229], v[76:79]
	v_mfma_f32_16x16x32_bf16 v[72:75], v[160:163], v[226:229], v[72:75]
	v_mfma_f32_16x16x32_bf16 v[116:119], v[164:167], v[198:201], v[116:119]
	v_mfma_f32_16x16x32_bf16 v[112:115], v[172:175], v[198:201], v[112:115]
	v_mfma_f32_16x16x32_bf16 v[100:103], v[164:167], v[206:209], v[100:103]
	v_mfma_f32_16x16x32_bf16 v[96:99], v[172:175], v[206:209], v[96:99]
	v_mfma_f32_16x16x32_bf16 v[84:87], v[164:167], v[214:217], v[84:87]
	v_mfma_f32_16x16x32_bf16 v[80:83], v[172:175], v[214:217], v[80:83]
	v_mfma_f32_16x16x32_bf16 v[68:71], v[164:167], v[222:225], v[68:71]
	v_mfma_f32_16x16x32_bf16 v[64:67], v[172:175], v[222:225], v[64:67]
	v_mfma_f32_16x16x32_bf16 v[116:119], v[168:171], v[202:205], v[116:119]
	v_mfma_f32_16x16x32_bf16 v[112:115], v[194:197], v[202:205], v[112:115]
	v_mfma_f32_16x16x32_bf16 v[100:103], v[168:171], v[210:213], v[100:103]
	v_mfma_f32_16x16x32_bf16 v[96:99], v[194:197], v[210:213], v[96:99]
	v_mfma_f32_16x16x32_bf16 v[84:87], v[168:171], v[218:221], v[84:87]
	v_mfma_f32_16x16x32_bf16 v[80:83], v[194:197], v[218:221], v[80:83]
	v_mfma_f32_16x16x32_bf16 v[68:71], v[168:171], v[226:229], v[68:71]
	v_mfma_f32_16x16x32_bf16 v[64:67], v[194:197], v[226:229], v[64:67]
	s_barrier
	s_add_i32 s54, s54, s20
	v_lshl_add_u64 v[178:179], s[48:49], 0, v[132:133]
	s_mov_b32 m0, s54
	ds_read_b128 v[198:201], v151 offset:16384
	ds_read_b128 v[202:205], v151 offset:17408
	ds_read_b128 v[206:209], v151 offset:18432
	ds_read_b128 v[210:213], v151 offset:19456
	ds_read_b128 v[214:217], v151 offset:20480
	ds_read_b128 v[218:221], v151 offset:21504
	ds_read_b128 v[222:225], v151 offset:22528
	ds_read_b128 v[226:229], v151 offset:23552
	global_load_lds_dwordx4 v[178:179], off
	s_add_i32 m0, s54, 0x2000
	s_add_u32 s54, s48, 0x40000
	v_lshl_add_u64 v[230:231], s[48:49], 0, v[128:129]
	s_addc_u32 s55, s49, 0
	s_add_i32 s56, s56, s20
	global_load_lds_dwordx4 v[230:231], off
	v_lshl_add_u64 v[232:233], s[54:55], 0, v[132:133]
	s_mov_b32 m0, s56
	v_lshl_add_u64 v[234:235], s[50:51], 0, v[130:131]
	global_load_lds_dwordx4 v[232:233], off
	v_lshl_add_u64 v[232:233], s[54:55], 0, v[128:129]
	s_add_i32 m0, s56, 0x2000
	s_nop 0
	global_load_lds_dwordx4 v[232:233], off
	v_lshl_add_u64 v[232:233], s[50:51], 0, v[134:135]
	s_mov_b32 m0, s21
	s_nop 0
	global_load_lds_dwordx4 v[232:233], off
	s_mov_b32 m0, s22
	s_nop 0
	global_load_lds_dwordx4 v[234:235], off
	s_waitcnt vmcnt(8)
	s_waitcnt lgkmcnt(0)
	s_barrier
	s_waitcnt lgkmcnt(0)
	v_mfma_f32_16x16x32_bf16 v[60:63], v[142:145], v[198:201], v[60:63]
	v_mfma_f32_16x16x32_bf16 v[56:59], v[156:159], v[198:201], v[56:59]
	v_mfma_f32_16x16x32_bf16 v[44:47], v[142:145], v[206:209], v[44:47]
	v_mfma_f32_16x16x32_bf16 v[40:43], v[156:159], v[206:209], v[40:43]
	v_mfma_f32_16x16x32_bf16 v[28:31], v[142:145], v[214:217], v[28:31]
	v_mfma_f32_16x16x32_bf16 v[24:27], v[156:159], v[214:217], v[24:27]
	v_mfma_f32_16x16x32_bf16 v[12:15], v[142:145], v[222:225], v[12:15]
	v_mfma_f32_16x16x32_bf16 v[8:11], v[156:159], v[222:225], v[8:11]
	v_mfma_f32_16x16x32_bf16 v[60:63], v[152:155], v[202:205], v[60:63]
	v_mfma_f32_16x16x32_bf16 v[56:59], v[160:163], v[202:205], v[56:59]
	v_mfma_f32_16x16x32_bf16 v[44:47], v[152:155], v[210:213], v[44:47]
	v_mfma_f32_16x16x32_bf16 v[40:43], v[160:163], v[210:213], v[40:43]
	v_mfma_f32_16x16x32_bf16 v[28:31], v[152:155], v[218:221], v[28:31]
	v_mfma_f32_16x16x32_bf16 v[24:27], v[160:163], v[218:221], v[24:27]
	v_mfma_f32_16x16x32_bf16 v[12:15], v[152:155], v[226:229], v[12:15]
	v_mfma_f32_16x16x32_bf16 v[8:11], v[160:163], v[226:229], v[8:11]
	v_mfma_f32_16x16x32_bf16 v[52:55], v[164:167], v[198:201], v[52:55]
	v_mfma_f32_16x16x32_bf16 v[48:51], v[172:175], v[198:201], v[48:51]
	v_mfma_f32_16x16x32_bf16 v[36:39], v[164:167], v[206:209], v[36:39]
	v_mfma_f32_16x16x32_bf16 v[32:35], v[172:175], v[206:209], v[32:35]
	v_mfma_f32_16x16x32_bf16 v[20:23], v[164:167], v[214:217], v[20:23]
	v_mfma_f32_16x16x32_bf16 v[16:19], v[172:175], v[214:217], v[16:19]
	v_mfma_f32_16x16x32_bf16 v[4:7], v[164:167], v[222:225], v[4:7]
	v_mfma_f32_16x16x32_bf16 v[0:3], v[172:175], v[222:225], v[0:3]
	v_mfma_f32_16x16x32_bf16 v[52:55], v[168:171], v[202:205], v[52:55]
	v_mfma_f32_16x16x32_bf16 v[48:51], v[194:197], v[202:205], v[48:51]
	v_mfma_f32_16x16x32_bf16 v[36:39], v[168:171], v[210:213], v[36:39]
	v_mfma_f32_16x16x32_bf16 v[32:35], v[194:197], v[210:213], v[32:35]
	v_mfma_f32_16x16x32_bf16 v[20:23], v[168:171], v[218:221], v[20:23]
	v_mfma_f32_16x16x32_bf16 v[16:19], v[194:197], v[218:221], v[16:19]
	v_mfma_f32_16x16x32_bf16 v[4:7], v[168:171], v[226:229], v[4:7]
	v_mfma_f32_16x16x32_bf16 v[0:3], v[194:197], v[226:229], v[0:3]
	s_barrier
; #define PG8_STAGE(bufoff, gbase, voff) do { _Pragma("unroll") for (int _i = 0; _i < 2; ++_i) \
;         __builtin_amdgcn_global_load_lds((const unsigned*)((const char*)(gbase) + (voff)[_i]), (PG8_LAS unsigned*)(lds + (bufoff) + ldsw + _i * 8192), 16, 0, 0); } while (0)
; #define PG8_LDA(dst, b, h) do { _Pragma("unroll") for (int m = 0; m < 4; ++m) _Pragma("unroll") for (int k = 0; k < 2; ++k) dst[m][k] = *(const PG8_LAS bf16x8*)(lds + PG8_SA(b, h) + aoff + m * 2048 + k * 1024); } while (0)
; #define PG8_LDB(dst, b, h) do { _Pragma("unroll") for (int n = 0; n < 2; ++n) _Pragma("unroll") for (int k = 0; k < 2; ++k) dst[n][k] = *(const PG8_LAS bf16x8*)(lds + PG8_SB(b, h) + boff + n * 2048 + k * 1024); } while (0)
; #define PG8_MMA(ai, bj, At, Bt) do { __builtin_amdgcn_s_setprio(1); _Pragma("unroll") for (int m = 0; m < 4; ++m) _Pragma("unroll") for (int n = 0; n < 2; ++n) _Pragma("unroll") for (int k = 0; k < 2; ++k) \
;         acc[ai][bj][m][n] = __builtin_amdgcn_mfma_f32_16x16x32_bf16(Bt[n][k], At[m][k], acc[ai][bj][m][n], 0, 0, 0); __builtin_amdgcn_s_setprio(0); } while (0)
; #define PG8_WAIT_V(n) asm volatile("s_waitcnt vmcnt(" #n ")" ::: "memory")
; #define PG8_WAIT_L(n) asm volatile("s_waitcnt lgkmcnt(" #n ")" ::: "memory")
; #define PG8_BAR __builtin_amdgcn_s_barrier()
; #define PG8_SCHED __builtin_amdgcn_sched_barrier(0)
; template <class Epi, class Sched, bool ALIGN_EPI = false, bool SP2 = false>
; __device__ __forceinline__ void gemm_phase(PG8_LAS unsigned char* lds, const Gemm g, const Sched& S, const Epi& E) {
;     ...
;             PG8_LDB(B0, 1, 0); PG8_LDB(B1, 1, 1); PG8_SCHED; PG8_LDA(At, 1, 0); PG8_STAGE(PG8_SA(0, 1), a2 + hstep, voffA);
;             PG8_WAIT_V(8); PG8_WAIT_L(0); PG8_BAR; PG8_MMA(0, 0, At, B0); PG8_MMA(0, 1, At, B1); PG8_BAR; PG8_SCHED;
	s_add_i32 s54, 0, 0x18000
	v_add_u32_e32 v141, s54, v148
	s_add_i32 s55, 0, 0x1c000
	ds_read_b128 v[142:145], v141
	ds_read_b128 v[152:155], v141 offset:1024
	ds_read_b128 v[156:159], v141 offset:2048
	ds_read_b128 v[160:163], v141 offset:3072
	v_add_u32_e32 v141, s55, v148
	ds_read_b128 v[164:167], v141
	ds_read_b128 v[168:171], v141 offset:1024
	ds_read_b128 v[172:175], v141 offset:2048
	ds_read_b128 v[194:197], v141 offset:3072
	s_add_u32 s50, s50, 0x40000
	s_addc_u32 s51, s51, 0
	s_mov_b32 m0, s23
	v_lshl_add_u64 v[236:237], s[50:51], 0, v[134:135]
	ds_read_b128 v[198:201], v151 offset:32768
	ds_read_b128 v[202:205], v151 offset:33792
	ds_read_b128 v[206:209], v151 offset:34816
	ds_read_b128 v[210:213], v151 offset:35840
	ds_read_b128 v[214:217], v151 offset:36864
	ds_read_b128 v[218:221], v151 offset:37888
	ds_read_b128 v[222:225], v151 offset:38912
	ds_read_b128 v[226:229], v151 offset:39936
	global_load_lds_dwordx4 v[236:237], off
	v_lshl_add_u64 v[236:237], s[50:51], 0, v[130:131]
	s_mov_b32 m0, s24
	s_nop 0
	global_load_lds_dwordx4 v[236:237], off
	s_waitcnt vmcnt(8)
	s_waitcnt lgkmcnt(0)
	s_barrier
	s_waitcnt lgkmcnt(0)
	v_mfma_f32_16x16x32_bf16 v[124:127], v[142:145], v[198:201], v[124:127]
	v_mfma_f32_16x16x32_bf16 v[120:123], v[156:159], v[198:201], v[120:123]
	v_mfma_f32_16x16x32_bf16 v[108:111], v[142:145], v[206:209], v[108:111]
	v_mfma_f32_16x16x32_bf16 v[104:107], v[156:159], v[206:209], v[104:107]
	v_mfma_f32_16x16x32_bf16 v[92:95], v[142:145], v[214:217], v[92:95]
	v_mfma_f32_16x16x32_bf16 v[88:91], v[156:159], v[214:217], v[88:91]
	v_mfma_f32_16x16x32_bf16 v[76:79], v[142:145], v[222:225], v[76:79]
	v_mfma_f32_16x16x32_bf16 v[72:75], v[156:159], v[222:225], v[72:75]
	v_mfma_f32_16x16x32_bf16 v[124:127], v[152:155], v[202:205], v[124:127]
	v_mfma_f32_16x16x32_bf16 v[120:123], v[160:163], v[202:205], v[120:123]
	v_mfma_f32_16x16x32_bf16 v[108:111], v[152:155], v[210:213], v[108:111]
	v_mfma_f32_16x16x32_bf16 v[104:107], v[160:163], v[210:213], v[104:107]
	v_mfma_f32_16x16x32_bf16 v[92:95], v[152:155], v[218:221], v[92:95]
	v_mfma_f32_16x16x32_bf16 v[88:91], v[160:163], v[218:221], v[88:91]
	v_mfma_f32_16x16x32_bf16 v[76:79], v[152:155], v[226:229], v[76:79]
	v_mfma_f32_16x16x32_bf16 v[72:75], v[160:163], v[226:229], v[72:75]
	v_mfma_f32_16x16x32_bf16 v[116:119], v[164:167], v[198:201], v[116:119]
	v_mfma_f32_16x16x32_bf16 v[112:115], v[172:175], v[198:201], v[112:115]
	v_mfma_f32_16x16x32_bf16 v[100:103], v[164:167], v[206:209], v[100:103]
	v_mfma_f32_16x16x32_bf16 v[96:99], v[172:175], v[206:209], v[96:99]
	v_mfma_f32_16x16x32_bf16 v[84:87], v[164:167], v[214:217], v[84:87]
	v_mfma_f32_16x16x32_bf16 v[80:83], v[172:175], v[214:217], v[80:83]
	v_mfma_f32_16x16x32_bf16 v[68:71], v[164:167], v[222:225], v[68:71]
	v_mfma_f32_16x16x32_bf16 v[64:67], v[172:175], v[222:225], v[64:67]
	v_mfma_f32_16x16x32_bf16 v[116:119], v[168:171], v[202:205], v[116:119]
	v_mfma_f32_16x16x32_bf16 v[112:115], v[194:197], v[202:205], v[112:115]
	v_mfma_f32_16x16x32_bf16 v[100:103], v[168:171], v[210:213], v[100:103]
	v_mfma_f32_16x16x32_bf16 v[96:99], v[194:197], v[210:213], v[96:99]
	v_mfma_f32_16x16x32_bf16 v[84:87], v[168:171], v[218:221], v[84:87]
	v_mfma_f32_16x16x32_bf16 v[80:83], v[194:197], v[218:221], v[80:83]
	v_mfma_f32_16x16x32_bf16 v[68:71], v[168:171], v[226:229], v[68:71]
	v_mfma_f32_16x16x32_bf16 v[64:67], v[194:197], v[226:229], v[64:67]
	s_barrier
; #define PG8_STAGE(bufoff, gbase, voff) do { _Pragma("unroll") for (int _i = 0; _i < 2; ++_i) \
;         __builtin_amdgcn_global_load_lds((const unsigned*)((const char*)(gbase) + (voff)[_i]), (PG8_LAS unsigned*)(lds + (bufoff) + ldsw + _i * 8192), 16, 0, 0); } while (0)
; #define PG8_LDA(dst, b, h) do { _Pragma("unroll") for (int m = 0; m < 4; ++m) _Pragma("unroll") for (int k = 0; k < 2; ++k) dst[m][k] = *(const PG8_LAS bf16x8*)(lds + PG8_SA(b, h) + aoff + m * 2048 + k * 1024); } while (0)
; #define PG8_MMA(ai, bj, At, Bt) do { __builtin_amdgcn_s_setprio(1); _Pragma("unroll") for (int m = 0; m < 4; ++m) _Pragma("unroll") for (int n = 0; n < 2; ++n) _Pragma("unroll") for (int k = 0; k < 2; ++k) \
;         acc[ai][bj][m][n] = __builtin_amdgcn_mfma_f32_16x16x32_bf16(Bt[n][k], At[m][k], acc[ai][bj][m][n], 0, 0, 0); __builtin_amdgcn_s_setprio(0); } while (0)
; #define PG8_WAIT_V(n) asm volatile("s_waitcnt vmcnt(" #n ")" ::: "memory")
; #define PG8_WAIT_L(n) asm volatile("s_waitcnt lgkmcnt(" #n ")" ::: "memory")
; #define PG8_BAR __builtin_amdgcn_s_barrier()
; #define PG8_SCHED __builtin_amdgcn_sched_barrier(0)
; template <class Epi, class Sched, bool ALIGN_EPI = false, bool SP2 = false>
; __device__ __forceinline__ void gemm_phase(PG8_LAS unsigned char* lds, const Gemm g, const Sched& S, const Epi& E) {
;     ...
;             PG8_LDA(At, 1, 1); PG8_STAGE(PG8_SB(1, 0), b3, voffB); PG8_STAGE(PG8_SB(1, 1), b3 + hstep, voffB); PG8_STAGE(PG8_SA(1, 0), a3, voffA);
;             PG8_WAIT_V(8); PG8_WAIT_L(0); PG8_BAR; PG8_MMA(1, 0, At, B0); PG8_MMA(1, 1, At, B1); PG8_BAR; PG8_SCHED;
;     ...
;         if constexpr (ALIGN_EPI) { if (wr == 0) PG8_BAR; }
	s_add_i32 s50, s54, s20
	v_lshl_add_u64 v[178:179], v[178:179], 0, s[36:37]
	s_mov_b32 m0, s50
	ds_read_b128 v[198:201], v151 offset:49152
	ds_read_b128 v[202:205], v151 offset:50176
	ds_read_b128 v[206:209], v151 offset:51200
	ds_read_b128 v[210:213], v151 offset:52224
	ds_read_b128 v[214:217], v151 offset:53248
	ds_read_b128 v[218:221], v151 offset:54272
	ds_read_b128 v[222:225], v151 offset:55296
	ds_read_b128 v[226:229], v151 offset:56320
	global_load_lds_dwordx4 v[178:179], off
	s_add_i32 m0, s50, 0x2000
	s_add_u32 s48, s48, 0x40080
	v_lshl_add_u64 v[178:179], v[230:231], 0, s[36:37]
	s_addc_u32 s49, s49, 0
	s_add_i32 s50, s55, s20
	global_load_lds_dwordx4 v[178:179], off
	v_lshl_add_u64 v[178:179], s[48:49], 0, v[132:133]
	s_mov_b32 m0, s50
	s_nop 0
	global_load_lds_dwordx4 v[178:179], off
	v_lshl_add_u64 v[178:179], s[48:49], 0, v[128:129]
	s_add_i32 m0, s50, 0x2000
	s_nop 0
	global_load_lds_dwordx4 v[178:179], off
	v_lshl_add_u64 v[178:179], v[232:233], 0, s[36:37]
	s_mov_b32 m0, s25
	s_nop 0
	global_load_lds_dwordx4 v[178:179], off
	v_lshl_add_u64 v[178:179], v[234:235], 0, s[36:37]
	s_mov_b32 m0, s28
	s_nop 0
	global_load_lds_dwordx4 v[178:179], off
	s_waitcnt vmcnt(8)
	s_waitcnt lgkmcnt(0)
	s_barrier
	s_waitcnt lgkmcnt(0)
	v_mfma_f32_16x16x32_bf16 v[60:63], v[142:145], v[198:201], v[60:63]
	v_mfma_f32_16x16x32_bf16 v[56:59], v[156:159], v[198:201], v[56:59]
	v_mfma_f32_16x16x32_bf16 v[44:47], v[142:145], v[206:209], v[44:47]
	v_mfma_f32_16x16x32_bf16 v[40:43], v[156:159], v[206:209], v[40:43]
	v_mfma_f32_16x16x32_bf16 v[28:31], v[142:145], v[214:217], v[28:31]
	v_mfma_f32_16x16x32_bf16 v[24:27], v[156:159], v[214:217], v[24:27]
	v_mfma_f32_16x16x32_bf16 v[12:15], v[142:145], v[222:225], v[12:15]
	v_mfma_f32_16x16x32_bf16 v[8:11], v[156:159], v[222:225], v[8:11]
	v_mfma_f32_16x16x32_bf16 v[60:63], v[152:155], v[202:205], v[60:63]
	v_mfma_f32_16x16x32_bf16 v[56:59], v[160:163], v[202:205], v[56:59]
	v_mfma_f32_16x16x32_bf16 v[44:47], v[152:155], v[210:213], v[44:47]
	v_mfma_f32_16x16x32_bf16 v[40:43], v[160:163], v[210:213], v[40:43]
	v_mfma_f32_16x16x32_bf16 v[28:31], v[152:155], v[218:221], v[28:31]
	v_mfma_f32_16x16x32_bf16 v[24:27], v[160:163], v[218:221], v[24:27]
	v_mfma_f32_16x16x32_bf16 v[12:15], v[152:155], v[226:229], v[12:15]
	v_mfma_f32_16x16x32_bf16 v[8:11], v[160:163], v[226:229], v[8:11]
	v_mfma_f32_16x16x32_bf16 v[52:55], v[164:167], v[198:201], v[52:55]
	v_mfma_f32_16x16x32_bf16 v[48:51], v[172:175], v[198:201], v[48:51]
	v_mfma_f32_16x16x32_bf16 v[36:39], v[164:167], v[206:209], v[36:39]
	v_mfma_f32_16x16x32_bf16 v[32:35], v[172:175], v[206:209], v[32:35]
	v_mfma_f32_16x16x32_bf16 v[20:23], v[164:167], v[214:217], v[20:23]
	v_mfma_f32_16x16x32_bf16 v[16:19], v[172:175], v[214:217], v[16:19]
	v_mfma_f32_16x16x32_bf16 v[4:7], v[164:167], v[222:225], v[4:7]
	v_mfma_f32_16x16x32_bf16 v[0:3], v[172:175], v[222:225], v[0:3]
	v_mfma_f32_16x16x32_bf16 v[52:55], v[168:171], v[202:205], v[52:55]
	v_mfma_f32_16x16x32_bf16 v[48:51], v[194:197], v[202:205], v[48:51]
	v_mfma_f32_16x16x32_bf16 v[36:39], v[168:171], v[210:213], v[36:39]
	v_mfma_f32_16x16x32_bf16 v[32:35], v[194:197], v[210:213], v[32:35]
	v_mfma_f32_16x16x32_bf16 v[20:23], v[168:171], v[218:221], v[20:23]
	v_mfma_f32_16x16x32_bf16 v[16:19], v[194:197], v[218:221], v[16:19]
	v_mfma_f32_16x16x32_bf16 v[4:7], v[168:171], v[226:229], v[4:7]
	v_mfma_f32_16x16x32_bf16 v[0:3], v[194:197], v[226:229], v[0:3]
	s_barrier
	s_add_i32 s53, s53, 2
	s_add_u32 s41, s41, 0x100
	s_addc_u32 s52, s52, 0
	s_add_u32 s46, s46, 0x100
	s_addc_u32 s47, s47, 0
	s_cmp_gt_u32 s53, 13
	s_cbranch_scc0 .LBB0_659
	s_setprio 0
	s_and_b64 vcc, exec, s[16:17]
	s_cbranch_vccz .LBB0_662
	s_barrier

; #define PG8_STAGE(bufoff, gbase, voff) do { _Pragma("unroll") for (int _i = 0; _i < 2; ++_i) \
;         __builtin_amdgcn_global_load_lds((const unsigned*)((const char*)(gbase) + (voff)[_i]), (PG8_LAS unsigned*)(lds + (bufoff) + ldsw + _i * 8192), 16, 0, 0); } while (0)
; #define PG8_LDA(dst, b, h) do { _Pragma("unroll") for (int m = 0; m < 4; ++m) _Pragma("unroll") for (int k = 0; k < 2; ++k) dst[m][k] = *(const PG8_LAS bf16x8*)(lds + PG8_SA(b, h) + aoff + m * 2048 + k * 1024); } while (0)
; #define PG8_LDB(dst, b, h) do { _Pragma("unroll") for (int n = 0; n < 2; ++n) _Pragma("unroll") for (int k = 0; k < 2; ++k) dst[n][k] = *(const PG8_LAS bf16x8*)(lds + PG8_SB(b, h) + boff + n * 2048 + k * 1024); } while (0)
; #define PG8_WAIT_V(n) asm volatile("s_waitcnt vmcnt(" #n ")" ::: "memory")
; #define PG8_WAIT_L(n) asm volatile("s_waitcnt lgkmcnt(" #n ")" ::: "memory")
; #define PG8_BAR __builtin_amdgcn_s_barrier()
; template <class Epi, class Sched, bool ALIGN_EPI = false, bool SP2 = false>
; __device__ __forceinline__ void gemm_phase(PG8_LAS unsigned char* lds, const Gemm g, const Sched& S, const Epi& E) {
;     ...
;         const bool has_next = S.next(ui + 1, nxt);
;         const char* nA = has_next ? (const char*)g.A + (size_t)nxt.pm * tstep : cA; const char* nB = has_next ? (const char*)g.Bt + (size_t)nxt.pn * tstep : cB;
;         for (int t = 0; t < nt; t += 2) {
;             const bool last = (t == nt - 2);
;             const char* a1 = cA + (size_t)(t + 1) * kstep;
;             const char* a2 = last ? nA : cA + (size_t)(t + 2) * kstep; const char* b2 = last ? nB : cB + (size_t)(t + 2) * kstep;
;             const char* a3 = a2 + kstep; const char* b3 = b2 + kstep;
;             if (last && has_next) S.a_ready(nxt);
;             if constexpr (SP2) {
;             PG8_LDB(B0, 0, 0); PG8_LDB(B1, 0, 1); PG8_SCHED; PG8_LDA(At, 0, 0); PG8_STAGE(PG8_SA(1, 1), a1 + hstep, voffA);
;             PG8_WAIT_V(8); PG8_WAIT_L(0); PG8_BAR; PG8_MMA(0, 0, At, B0); PG8_MMA(0, 1, At, B1); PG8_BAR; PG8_SCHED;
;     ...
; #pragma unroll
;         for (int a = 0; a < 2; ++a)
; #pragma unroll
;             for (int b = 0; b < 2; ++b)
; #pragma unroll
;                 for (int m = 0; m < 4; ++m)
; #pragma unroll
;                     for (int n = 0; n < 2; ++n) acc[a][b][m][n] = (f32x4){0.f, 0.f, 0.f, 0.f};
;         cur = nxt; cA = nA; cB = nB; ++ui;
.LBB0_743:
	s_ashr_i32 s51, s50, 31
	s_lshl_b64 s[34:35], s[50:51], 21
	s_add_u32 s52, s2, s34
	s_addc_u32 s53, s3, s35
	s_and_b64 s[34:35], s[6:7], exec
	s_cselect_b32 s33, s53, s39
	s_cselect_b32 s34, s52, s38
	s_ashr_i32 s49, s48, 31
	s_lshl_b64 s[54:55], s[48:49], 21
	s_add_u32 s54, s10, s54
	s_addc_u32 s55, s11, s55
	s_and_b64 s[56:57], s[6:7], exec
	s_cselect_b32 s35, s55, s5
	s_cselect_b32 s49, s54, s4
	s_add_u32 s51, s4, 0x100
	s_addc_u32 s58, s5, 0
	s_add_u32 s4, s38, 0x100080
	v_mov_b32_e32 v0, 0
	s_addc_u32 s5, s39, 0
	s_mov_b32 s59, -2
	s_waitcnt lgkmcnt(0)
	v_mov_b32_e32 v1, v0
	v_mov_b32_e32 v2, v0
	v_mov_b32_e32 v3, v0
	v_mov_b32_e32 v4, v0
	v_mov_b32_e32 v5, v0
	v_mov_b32_e32 v6, v0
	v_mov_b32_e32 v7, v0
	v_mov_b32_e32 v16, v0
	v_mov_b32_e32 v17, v0
	v_mov_b32_e32 v18, v0
	v_mov_b32_e32 v19, v0
	v_mov_b32_e32 v20, v0
	v_mov_b32_e32 v21, v0
	v_mov_b32_e32 v22, v0
	v_mov_b32_e32 v23, v0
	v_mov_b32_e32 v32, v0
	v_mov_b32_e32 v33, v0
	v_mov_b32_e32 v34, v0
	v_mov_b32_e32 v35, v0
	v_mov_b32_e32 v36, v0
	v_mov_b32_e32 v37, v0
	v_mov_b32_e32 v38, v0
	v_mov_b32_e32 v39, v0
	v_mov_b32_e32 v48, v0
	v_mov_b32_e32 v49, v0
	v_mov_b32_e32 v50, v0
	v_mov_b32_e32 v51, v0
	v_mov_b32_e32 v52, v0
	v_mov_b32_e32 v53, v0
	v_mov_b32_e32 v54, v0
	v_mov_b32_e32 v55, v0
	v_mov_b32_e32 v8, v0
	v_mov_b32_e32 v9, v0
	v_mov_b32_e32 v10, v0
	v_mov_b32_e32 v11, v0
	v_mov_b32_e32 v12, v0
	v_mov_b32_e32 v13, v0
	v_mov_b32_e32 v14, v0
	v_mov_b32_e32 v15, v0
	v_mov_b32_e32 v24, v0
	v_mov_b32_e32 v25, v0
	v_mov_b32_e32 v26, v0
	v_mov_b32_e32 v27, v0
	v_mov_b32_e32 v28, v0
	v_mov_b32_e32 v29, v0
	v_mov_b32_e32 v30, v0
	v_mov_b32_e32 v31, v0
	v_mov_b32_e32 v40, v0
	v_mov_b32_e32 v41, v0
	v_mov_b32_e32 v42, v0
	v_mov_b32_e32 v43, v0
	v_mov_b32_e32 v44, v0
	v_mov_b32_e32 v45, v0
	v_mov_b32_e32 v46, v0
	v_mov_b32_e32 v47, v0
	v_mov_b32_e32 v56, v0
	v_mov_b32_e32 v57, v0
	v_mov_b32_e32 v58, v0
	v_mov_b32_e32 v59, v0
	v_mov_b32_e32 v60, v0
	v_mov_b32_e32 v61, v0
	v_mov_b32_e32 v62, v0
	v_mov_b32_e32 v63, v0
	v_mov_b32_e32 v64, v0
	v_mov_b32_e32 v65, v0
	v_mov_b32_e32 v66, v0
	v_mov_b32_e32 v67, v0
	v_mov_b32_e32 v68, v0
	v_mov_b32_e32 v69, v0
	v_mov_b32_e32 v70, v0
	v_mov_b32_e32 v71, v0
	v_mov_b32_e32 v80, v0
	v_mov_b32_e32 v81, v0
	v_mov_b32_e32 v82, v0
	v_mov_b32_e32 v83, v0
	v_mov_b32_e32 v84, v0
	v_mov_b32_e32 v85, v0
	v_mov_b32_e32 v86, v0
	v_mov_b32_e32 v87, v0
	v_mov_b32_e32 v96, v0
	v_mov_b32_e32 v97, v0
	v_mov_b32_e32 v98, v0
	v_mov_b32_e32 v99, v0
	v_mov_b32_e32 v100, v0
	v_mov_b32_e32 v101, v0
	v_mov_b32_e32 v102, v0
	v_mov_b32_e32 v103, v0
	v_mov_b32_e32 v112, v0
	v_mov_b32_e32 v113, v0
	v_mov_b32_e32 v114, v0
	v_mov_b32_e32 v115, v0
	v_mov_b32_e32 v116, v0
	v_mov_b32_e32 v117, v0
	v_mov_b32_e32 v118, v0
	v_mov_b32_e32 v119, v0
	v_mov_b32_e32 v72, v0
	v_mov_b32_e32 v73, v0
	v_mov_b32_e32 v74, v0
	v_mov_b32_e32 v75, v0
	v_mov_b32_e32 v76, v0
	v_mov_b32_e32 v77, v0
	v_mov_b32_e32 v78, v0
	v_mov_b32_e32 v79, v0
	v_mov_b32_e32 v88, v0
	v_mov_b32_e32 v89, v0
	v_mov_b32_e32 v90, v0
	v_mov_b32_e32 v91, v0
	v_mov_b32_e32 v92, v0
	v_mov_b32_e32 v93, v0
	v_mov_b32_e32 v94, v0
	v_mov_b32_e32 v95, v0
	v_mov_b32_e32 v104, v0
	v_mov_b32_e32 v105, v0
	v_mov_b32_e32 v106, v0
	v_mov_b32_e32 v107, v0
	v_mov_b32_e32 v108, v0
	v_mov_b32_e32 v109, v0
	v_mov_b32_e32 v110, v0
	v_mov_b32_e32 v111, v0
	v_mov_b32_e32 v124, v0
	v_mov_b32_e32 v125, v0
	v_mov_b32_e32 v126, v0
	v_mov_b32_e32 v127, v0
	v_mov_b32_e32 v128, v0
	v_mov_b32_e32 v129, v0
	v_mov_b32_e32 v130, v0
	v_mov_b32_e32 v131, v0
	s_cmp_eq_u32 s101, 0
	s_cbranch_scc1 .Lsp_skip4
	s_setprio 1
.Lsp_skip4:
.LBB0_744:
	s_add_u32 s38, s4, 0xfff00080
	s_addc_u32 s39, s5, -1
	s_add_i32 s60, 0, 0x10000
	s_cmp_eq_u32 s59, 60
	s_cselect_b32 s57, s33, s39
	s_cselect_b32 s56, s34, s38
	s_cselect_b32 s39, s35, s58
	s_cselect_b32 s38, s49, s51
	s_add_i32 s62, 0, 0x14000
	v_add_u32_e32 v140, s60, v205
	v_add_u32_e32 v168, s62, v205
	ds_read_b128 v[120:123], v140
	ds_read_b128 v[132:135], v140 offset:1024
	ds_read_b128 v[136:139], v140 offset:2048
	ds_read_b128 v[140:143], v140 offset:3072
	ds_read_b128 v[144:147], v168
	ds_read_b128 v[148:151], v168 offset:1024
	ds_read_b128 v[152:155], v168 offset:2048
	ds_read_b128 v[168:171], v168 offset:3072
	v_lshl_add_u64 v[178:179], s[4:5], 0, v[166:167]
	s_add_i32 m0, s21, 0xc000
	ds_read_b128 v[172:175], v207
	ds_read_b128 v[194:197], v207 offset:1024
	ds_read_b128 v[198:201], v207 offset:2048
	ds_read_b128 v[208:211], v207 offset:3072
	ds_read_b128 v[212:215], v207 offset:4096
	ds_read_b128 v[216:219], v207 offset:5120
	ds_read_b128 v[220:223], v207 offset:6144
	ds_read_b128 v[224:227], v207 offset:7168
	global_load_lds_dwordx4 v[178:179], off
	v_lshl_add_u64 v[178:179], s[4:5], 0, v[164:165]
	s_add_i32 m0, s21, 0xe000
	s_nop 0
	global_load_lds_dwordx4 v[178:179], off
	s_waitcnt vmcnt(8)
	s_waitcnt lgkmcnt(0)
	s_barrier
; #define PG8_STAGE(bufoff, gbase, voff) do { _Pragma("unroll") for (int _i = 0; _i < 2; ++_i) \
;         __builtin_amdgcn_global_load_lds((const unsigned*)((const char*)(gbase) + (voff)[_i]), (PG8_LAS unsigned*)(lds + (bufoff) + ldsw + _i * 8192), 16, 0, 0); } while (0)
; #define PG8_LDA(dst, b, h) do { _Pragma("unroll") for (int m = 0; m < 4; ++m) _Pragma("unroll") for (int k = 0; k < 2; ++k) dst[m][k] = *(const PG8_LAS bf16x8*)(lds + PG8_SA(b, h) + aoff + m * 2048 + k * 1024); } while (0)
; #define PG8_MMA(ai, bj, At, Bt) do { __builtin_amdgcn_s_setprio(1); _Pragma("unroll") for (int m = 0; m < 4; ++m) _Pragma("unroll") for (int n = 0; n < 2; ++n) _Pragma("unroll") for (int k = 0; k < 2; ++k) \
;         acc[ai][bj][m][n] = __builtin_amdgcn_mfma_f32_16x16x32_bf16(Bt[n][k], At[m][k], acc[ai][bj][m][n], 0, 0, 0); __builtin_amdgcn_s_setprio(0); } while (0)
; #define PG8_WAIT_V(n) asm volatile("s_waitcnt vmcnt(" #n ")" ::: "memory")
; #define PG8_WAIT_L(n) asm volatile("s_waitcnt lgkmcnt(" #n ")" ::: "memory")
; #define PG8_BAR __builtin_amdgcn_s_barrier()
; #define PG8_SCHED __builtin_amdgcn_sched_barrier(0)
; template <class Epi, class Sched, bool ALIGN_EPI = false, bool SP2 = false>
; __device__ __forceinline__ void gemm_phase(PG8_LAS unsigned char* lds, const Gemm g, const Sched& S, const Epi& E) {
;     ...
;             PG8_WAIT_V(8); PG8_WAIT_L(0); PG8_BAR; PG8_MMA(0, 0, At, B0); PG8_MMA(0, 1, At, B1); PG8_BAR; PG8_SCHED;
;             PG8_LDA(At, 0, 1); PG8_STAGE(PG8_SB(0, 0), b2, voffB); PG8_STAGE(PG8_SB(0, 1), b2 + hstep, voffB); PG8_STAGE(PG8_SA(0, 0), a2, voffA);
;             PG8_WAIT_V(8); PG8_WAIT_L(0); PG8_BAR; PG8_MMA(1, 0, At, B0); PG8_MMA(1, 1, At, B1); PG8_BAR; PG8_SCHED;
	s_waitcnt lgkmcnt(0)
	v_mfma_f32_16x16x32_bf16 v[128:131], v[120:123], v[172:175], v[128:131]
	v_mfma_f32_16x16x32_bf16 v[124:127], v[136:139], v[172:175], v[124:127]
	v_mfma_f32_16x16x32_bf16 v[108:111], v[120:123], v[198:201], v[108:111]
	v_mfma_f32_16x16x32_bf16 v[104:107], v[136:139], v[198:201], v[104:107]
	v_mfma_f32_16x16x32_bf16 v[92:95], v[120:123], v[212:215], v[92:95]
	v_mfma_f32_16x16x32_bf16 v[88:91], v[136:139], v[212:215], v[88:91]
	v_mfma_f32_16x16x32_bf16 v[76:79], v[120:123], v[220:223], v[76:79]
	v_mfma_f32_16x16x32_bf16 v[72:75], v[136:139], v[220:223], v[72:75]
	v_mfma_f32_16x16x32_bf16 v[128:131], v[132:135], v[194:197], v[128:131]
	v_mfma_f32_16x16x32_bf16 v[124:127], v[140:143], v[194:197], v[124:127]
	v_mfma_f32_16x16x32_bf16 v[108:111], v[132:135], v[208:211], v[108:111]
	v_mfma_f32_16x16x32_bf16 v[104:107], v[140:143], v[208:211], v[104:107]
	v_mfma_f32_16x16x32_bf16 v[92:95], v[132:135], v[216:219], v[92:95]
	v_mfma_f32_16x16x32_bf16 v[88:91], v[140:143], v[216:219], v[88:91]
	v_mfma_f32_16x16x32_bf16 v[76:79], v[132:135], v[224:227], v[76:79]
	v_mfma_f32_16x16x32_bf16 v[72:75], v[140:143], v[224:227], v[72:75]
	v_mfma_f32_16x16x32_bf16 v[116:119], v[144:147], v[172:175], v[116:119]
	v_mfma_f32_16x16x32_bf16 v[112:115], v[152:155], v[172:175], v[112:115]
	v_mfma_f32_16x16x32_bf16 v[100:103], v[144:147], v[198:201], v[100:103]
	v_mfma_f32_16x16x32_bf16 v[96:99], v[152:155], v[198:201], v[96:99]
	v_mfma_f32_16x16x32_bf16 v[84:87], v[144:147], v[212:215], v[84:87]
	v_mfma_f32_16x16x32_bf16 v[80:83], v[152:155], v[212:215], v[80:83]
	v_mfma_f32_16x16x32_bf16 v[68:71], v[144:147], v[220:223], v[68:71]
	v_mfma_f32_16x16x32_bf16 v[64:67], v[152:155], v[220:223], v[64:67]
	v_mfma_f32_16x16x32_bf16 v[116:119], v[148:151], v[194:197], v[116:119]
	v_mfma_f32_16x16x32_bf16 v[112:115], v[168:171], v[194:197], v[112:115]
	v_mfma_f32_16x16x32_bf16 v[100:103], v[148:151], v[208:211], v[100:103]
	v_mfma_f32_16x16x32_bf16 v[96:99], v[168:171], v[208:211], v[96:99]
	v_mfma_f32_16x16x32_bf16 v[84:87], v[148:151], v[216:219], v[84:87]
	v_mfma_f32_16x16x32_bf16 v[80:83], v[168:171], v[216:219], v[80:83]
	v_mfma_f32_16x16x32_bf16 v[68:71], v[148:151], v[224:227], v[68:71]
	v_mfma_f32_16x16x32_bf16 v[64:67], v[168:171], v[224:227], v[64:67]
	s_barrier
	s_add_i32 s60, s60, s20
	v_lshl_add_u64 v[178:179], s[38:39], 0, v[160:161]
	s_mov_b32 m0, s60
	ds_read_b128 v[172:175], v207 offset:16384
	ds_read_b128 v[194:197], v207 offset:17408
	ds_read_b128 v[198:201], v207 offset:18432
	ds_read_b128 v[208:211], v207 offset:19456
	ds_read_b128 v[212:215], v207 offset:20480
	ds_read_b128 v[216:219], v207 offset:21504
	ds_read_b128 v[220:223], v207 offset:22528
	ds_read_b128 v[224:227], v207 offset:23552
	global_load_lds_dwordx4 v[178:179], off
	s_add_i32 m0, s60, 0x2000
	s_add_u32 s60, s38, 0x100000
	v_lshl_add_u64 v[202:203], s[38:39], 0, v[156:157]
	s_addc_u32 s61, s39, 0
	s_add_i32 s62, s62, s20
	global_load_lds_dwordx4 v[202:203], off
	v_lshl_add_u64 v[228:229], s[60:61], 0, v[160:161]
	s_mov_b32 m0, s62
	v_lshl_add_u64 v[230:231], s[56:57], 0, v[158:159]
	global_load_lds_dwordx4 v[228:229], off
	v_lshl_add_u64 v[228:229], s[60:61], 0, v[156:157]
	s_add_i32 m0, s62, 0x2000
	s_nop 0
	global_load_lds_dwordx4 v[228:229], off
	v_lshl_add_u64 v[228:229], s[56:57], 0, v[162:163]
	s_mov_b32 m0, s21
	s_nop 0
	global_load_lds_dwordx4 v[228:229], off
	s_mov_b32 m0, s22
	s_nop 0
	global_load_lds_dwordx4 v[230:231], off
	s_waitcnt vmcnt(8)
	s_waitcnt lgkmcnt(0)
	s_barrier
	s_waitcnt lgkmcnt(0)
	v_mfma_f32_16x16x32_bf16 v[60:63], v[120:123], v[172:175], v[60:63]
	v_mfma_f32_16x16x32_bf16 v[56:59], v[136:139], v[172:175], v[56:59]
	v_mfma_f32_16x16x32_bf16 v[44:47], v[120:123], v[198:201], v[44:47]
	v_mfma_f32_16x16x32_bf16 v[40:43], v[136:139], v[198:201], v[40:43]
	v_mfma_f32_16x16x32_bf16 v[28:31], v[120:123], v[212:215], v[28:31]
	v_mfma_f32_16x16x32_bf16 v[24:27], v[136:139], v[212:215], v[24:27]
	v_mfma_f32_16x16x32_bf16 v[12:15], v[120:123], v[220:223], v[12:15]
	v_mfma_f32_16x16x32_bf16 v[8:11], v[136:139], v[220:223], v[8:11]
	v_mfma_f32_16x16x32_bf16 v[60:63], v[132:135], v[194:197], v[60:63]
	v_mfma_f32_16x16x32_bf16 v[56:59], v[140:143], v[194:197], v[56:59]
	v_mfma_f32_16x16x32_bf16 v[44:47], v[132:135], v[208:211], v[44:47]
	v_mfma_f32_16x16x32_bf16 v[40:43], v[140:143], v[208:211], v[40:43]
	v_mfma_f32_16x16x32_bf16 v[28:31], v[132:135], v[216:219], v[28:31]
	v_mfma_f32_16x16x32_bf16 v[24:27], v[140:143], v[216:219], v[24:27]
	v_mfma_f32_16x16x32_bf16 v[12:15], v[132:135], v[224:227], v[12:15]
	v_mfma_f32_16x16x32_bf16 v[8:11], v[140:143], v[224:227], v[8:11]
	v_mfma_f32_16x16x32_bf16 v[52:55], v[144:147], v[172:175], v[52:55]
	v_mfma_f32_16x16x32_bf16 v[48:51], v[152:155], v[172:175], v[48:51]
	v_mfma_f32_16x16x32_bf16 v[36:39], v[144:147], v[198:201], v[36:39]
	v_mfma_f32_16x16x32_bf16 v[32:35], v[152:155], v[198:201], v[32:35]
	v_mfma_f32_16x16x32_bf16 v[20:23], v[144:147], v[212:215], v[20:23]
	v_mfma_f32_16x16x32_bf16 v[16:19], v[152:155], v[212:215], v[16:19]
	v_mfma_f32_16x16x32_bf16 v[4:7], v[144:147], v[220:223], v[4:7]
	v_mfma_f32_16x16x32_bf16 v[0:3], v[152:155], v[220:223], v[0:3]
	v_mfma_f32_16x16x32_bf16 v[52:55], v[148:151], v[194:197], v[52:55]
	v_mfma_f32_16x16x32_bf16 v[48:51], v[168:171], v[194:197], v[48:51]
	v_mfma_f32_16x16x32_bf16 v[36:39], v[148:151], v[208:211], v[36:39]
	v_mfma_f32_16x16x32_bf16 v[32:35], v[168:171], v[208:211], v[32:35]
	v_mfma_f32_16x16x32_bf16 v[20:23], v[148:151], v[216:219], v[20:23]
	v_mfma_f32_16x16x32_bf16 v[16:19], v[168:171], v[216:219], v[16:19]
	v_mfma_f32_16x16x32_bf16 v[4:7], v[148:151], v[224:227], v[4:7]
	v_mfma_f32_16x16x32_bf16 v[0:3], v[168:171], v[224:227], v[0:3]
	s_barrier
; #define PG8_STAGE(bufoff, gbase, voff) do { _Pragma("unroll") for (int _i = 0; _i < 2; ++_i) \
;         __builtin_amdgcn_global_load_lds((const unsigned*)((const char*)(gbase) + (voff)[_i]), (PG8_LAS unsigned*)(lds + (bufoff) + ldsw + _i * 8192), 16, 0, 0); } while (0)
; #define PG8_LDA(dst, b, h) do { _Pragma("unroll") for (int m = 0; m < 4; ++m) _Pragma("unroll") for (int k = 0; k < 2; ++k) dst[m][k] = *(const PG8_LAS bf16x8*)(lds + PG8_SA(b, h) + aoff + m * 2048 + k * 1024); } while (0)
; #define PG8_LDB(dst, b, h) do { _Pragma("unroll") for (int n = 0; n < 2; ++n) _Pragma("unroll") for (int k = 0; k < 2; ++k) dst[n][k] = *(const PG8_LAS bf16x8*)(lds + PG8_SB(b, h) + boff + n * 2048 + k * 1024); } while (0)
; #define PG8_MMA(ai, bj, At, Bt) do { __builtin_amdgcn_s_setprio(1); _Pragma("unroll") for (int m = 0; m < 4; ++m) _Pragma("unroll") for (int n = 0; n < 2; ++n) _Pragma("unroll") for (int k = 0; k < 2; ++k) \
;         acc[ai][bj][m][n] = __builtin_amdgcn_mfma_f32_16x16x32_bf16(Bt[n][k], At[m][k], acc[ai][bj][m][n], 0, 0, 0); __builtin_amdgcn_s_setprio(0); } while (0)
; #define PG8_WAIT_V(n) asm volatile("s_waitcnt vmcnt(" #n ")" ::: "memory")
; #define PG8_WAIT_L(n) asm volatile("s_waitcnt lgkmcnt(" #n ")" ::: "memory")
; #define PG8_BAR __builtin_amdgcn_s_barrier()
; #define PG8_SCHED __builtin_amdgcn_sched_barrier(0)
; template <class Epi, class Sched, bool ALIGN_EPI = false, bool SP2 = false>
; __device__ __forceinline__ void gemm_phase(PG8_LAS unsigned char* lds, const Gemm g, const Sched& S, const Epi& E) {
;     ...
;             PG8_LDB(B0, 1, 0); PG8_LDB(B1, 1, 1); PG8_SCHED; PG8_LDA(At, 1, 0); PG8_STAGE(PG8_SA(0, 1), a2 + hstep, voffA);
;             PG8_WAIT_V(8); PG8_WAIT_L(0); PG8_BAR; PG8_MMA(0, 0, At, B0); PG8_MMA(0, 1, At, B1); PG8_BAR; PG8_SCHED;
	s_add_i32 s60, 0, 0x18000
	s_add_i32 s61, 0, 0x1c000
	v_add_u32_e32 v140, s60, v205
	v_add_u32_e32 v168, s61, v205
	ds_read_b128 v[120:123], v140
	ds_read_b128 v[132:135], v140 offset:1024
	ds_read_b128 v[136:139], v140 offset:2048
	ds_read_b128 v[140:143], v140 offset:3072
	ds_read_b128 v[144:147], v168
	ds_read_b128 v[148:151], v168 offset:1024
	ds_read_b128 v[152:155], v168 offset:2048
	ds_read_b128 v[168:171], v168 offset:3072
	s_add_u32 s56, s56, 0x100000
	s_addc_u32 s57, s57, 0
	s_mov_b32 m0, s23
	v_lshl_add_u64 v[232:233], s[56:57], 0, v[162:163]
	ds_read_b128 v[172:175], v207 offset:32768
	ds_read_b128 v[194:197], v207 offset:33792
	ds_read_b128 v[198:201], v207 offset:34816
	ds_read_b128 v[208:211], v207 offset:35840
	ds_read_b128 v[212:215], v207 offset:36864
	ds_read_b128 v[216:219], v207 offset:37888
	ds_read_b128 v[220:223], v207 offset:38912
	ds_read_b128 v[224:227], v207 offset:39936
	global_load_lds_dwordx4 v[232:233], off
	v_lshl_add_u64 v[232:233], s[56:57], 0, v[158:159]
	s_mov_b32 m0, s24
	s_nop 0
	global_load_lds_dwordx4 v[232:233], off
	s_waitcnt vmcnt(8)
	s_waitcnt lgkmcnt(0)
	s_barrier
	s_waitcnt lgkmcnt(0)
	v_mfma_f32_16x16x32_bf16 v[128:131], v[120:123], v[172:175], v[128:131]
	v_mfma_f32_16x16x32_bf16 v[124:127], v[136:139], v[172:175], v[124:127]
	v_mfma_f32_16x16x32_bf16 v[108:111], v[120:123], v[198:201], v[108:111]
	v_mfma_f32_16x16x32_bf16 v[104:107], v[136:139], v[198:201], v[104:107]
	v_mfma_f32_16x16x32_bf16 v[92:95], v[120:123], v[212:215], v[92:95]
	v_mfma_f32_16x16x32_bf16 v[88:91], v[136:139], v[212:215], v[88:91]
	v_mfma_f32_16x16x32_bf16 v[76:79], v[120:123], v[220:223], v[76:79]
	v_mfma_f32_16x16x32_bf16 v[72:75], v[136:139], v[220:223], v[72:75]
	v_mfma_f32_16x16x32_bf16 v[128:131], v[132:135], v[194:197], v[128:131]
	v_mfma_f32_16x16x32_bf16 v[124:127], v[140:143], v[194:197], v[124:127]
	v_mfma_f32_16x16x32_bf16 v[108:111], v[132:135], v[208:211], v[108:111]
	v_mfma_f32_16x16x32_bf16 v[104:107], v[140:143], v[208:211], v[104:107]
	v_mfma_f32_16x16x32_bf16 v[92:95], v[132:135], v[216:219], v[92:95]
	v_mfma_f32_16x16x32_bf16 v[88:91], v[140:143], v[216:219], v[88:91]
	v_mfma_f32_16x16x32_bf16 v[76:79], v[132:135], v[224:227], v[76:79]
	v_mfma_f32_16x16x32_bf16 v[72:75], v[140:143], v[224:227], v[72:75]
	v_mfma_f32_16x16x32_bf16 v[116:119], v[144:147], v[172:175], v[116:119]
	v_mfma_f32_16x16x32_bf16 v[112:115], v[152:155], v[172:175], v[112:115]
	v_mfma_f32_16x16x32_bf16 v[100:103], v[144:147], v[198:201], v[100:103]
	v_mfma_f32_16x16x32_bf16 v[96:99], v[152:155], v[198:201], v[96:99]
	v_mfma_f32_16x16x32_bf16 v[84:87], v[144:147], v[212:215], v[84:87]
	v_mfma_f32_16x16x32_bf16 v[80:83], v[152:155], v[212:215], v[80:83]
	v_mfma_f32_16x16x32_bf16 v[68:71], v[144:147], v[220:223], v[68:71]
	v_mfma_f32_16x16x32_bf16 v[64:67], v[152:155], v[220:223], v[64:67]
	v_mfma_f32_16x16x32_bf16 v[116:119], v[148:151], v[194:197], v[116:119]
	v_mfma_f32_16x16x32_bf16 v[112:115], v[168:171], v[194:197], v[112:115]
	v_mfma_f32_16x16x32_bf16 v[100:103], v[148:151], v[208:211], v[100:103]
	v_mfma_f32_16x16x32_bf16 v[96:99], v[168:171], v[208:211], v[96:99]
	v_mfma_f32_16x16x32_bf16 v[84:87], v[148:151], v[216:219], v[84:87]
	v_mfma_f32_16x16x32_bf16 v[80:83], v[168:171], v[216:219], v[80:83]
	v_mfma_f32_16x16x32_bf16 v[68:71], v[148:151], v[224:227], v[68:71]
	v_mfma_f32_16x16x32_bf16 v[64:67], v[168:171], v[224:227], v[64:67]
	s_barrier
; #define PG8_STAGE(bufoff, gbase, voff) do { _Pragma("unroll") for (int _i = 0; _i < 2; ++_i) \
;         __builtin_amdgcn_global_load_lds((const unsigned*)((const char*)(gbase) + (voff)[_i]), (PG8_LAS unsigned*)(lds + (bufoff) + ldsw + _i * 8192), 16, 0, 0); } while (0)
; #define PG8_LDA(dst, b, h) do { _Pragma("unroll") for (int m = 0; m < 4; ++m) _Pragma("unroll") for (int k = 0; k < 2; ++k) dst[m][k] = *(const PG8_LAS bf16x8*)(lds + PG8_SA(b, h) + aoff + m * 2048 + k * 1024); } while (0)
; #define PG8_MMA(ai, bj, At, Bt) do { __builtin_amdgcn_s_setprio(1); _Pragma("unroll") for (int m = 0; m < 4; ++m) _Pragma("unroll") for (int n = 0; n < 2; ++n) _Pragma("unroll") for (int k = 0; k < 2; ++k) \
;         acc[ai][bj][m][n] = __builtin_amdgcn_mfma_f32_16x16x32_bf16(Bt[n][k], At[m][k], acc[ai][bj][m][n], 0, 0, 0); __builtin_amdgcn_s_setprio(0); } while (0)
; #define PG8_WAIT_V(n) asm volatile("s_waitcnt vmcnt(" #n ")" ::: "memory")
; #define PG8_WAIT_L(n) asm volatile("s_waitcnt lgkmcnt(" #n ")" ::: "memory")
; #define PG8_BAR __builtin_amdgcn_s_barrier()
; #define PG8_SCHED __builtin_amdgcn_sched_barrier(0)
; template <class Epi, class Sched, bool ALIGN_EPI = false, bool SP2 = false>
; __device__ __forceinline__ void gemm_phase(PG8_LAS unsigned char* lds, const Gemm g, const Sched& S, const Epi& E) {
;     ...
;             PG8_LDA(At, 1, 1); PG8_STAGE(PG8_SB(1, 0), b3, voffB); PG8_STAGE(PG8_SB(1, 1), b3 + hstep, voffB); PG8_STAGE(PG8_SA(1, 0), a3, voffA);
;             PG8_WAIT_V(8); PG8_WAIT_L(0); PG8_BAR; PG8_MMA(1, 0, At, B0); PG8_MMA(1, 1, At, B1); PG8_BAR; PG8_SCHED;
;     ...
;         if constexpr (ALIGN_EPI) { if (wr == 0) PG8_BAR; }
	s_add_i32 s56, s60, s20
	v_lshl_add_u64 v[178:179], v[178:179], 0, s[36:37]
	s_mov_b32 m0, s56
	ds_read_b128 v[172:175], v207 offset:49152
	ds_read_b128 v[194:197], v207 offset:50176
	ds_read_b128 v[198:201], v207 offset:51200
	ds_read_b128 v[208:211], v207 offset:52224
	ds_read_b128 v[212:215], v207 offset:53248
	ds_read_b128 v[216:219], v207 offset:54272
	ds_read_b128 v[220:223], v207 offset:55296
	ds_read_b128 v[224:227], v207 offset:56320
	global_load_lds_dwordx4 v[178:179], off
	s_add_i32 m0, s56, 0x2000
	s_add_u32 s38, s38, 0x100080
	v_lshl_add_u64 v[178:179], v[202:203], 0, s[36:37]
	s_addc_u32 s39, s39, 0
	s_add_i32 s56, s61, s20
	global_load_lds_dwordx4 v[178:179], off
	v_lshl_add_u64 v[178:179], s[38:39], 0, v[160:161]
	s_mov_b32 m0, s56
	s_nop 0
	global_load_lds_dwordx4 v[178:179], off
	v_lshl_add_u64 v[178:179], s[38:39], 0, v[156:157]
	s_add_i32 m0, s56, 0x2000
	s_nop 0
	global_load_lds_dwordx4 v[178:179], off
	v_lshl_add_u64 v[178:179], v[228:229], 0, s[36:37]
	s_mov_b32 m0, s29
	s_nop 0
	global_load_lds_dwordx4 v[178:179], off
	v_lshl_add_u64 v[178:179], v[230:231], 0, s[36:37]
	s_mov_b32 m0, s30
	s_nop 0
	global_load_lds_dwordx4 v[178:179], off
	s_waitcnt vmcnt(8)
	s_waitcnt lgkmcnt(0)
	s_barrier
	s_waitcnt lgkmcnt(0)
	v_mfma_f32_16x16x32_bf16 v[60:63], v[120:123], v[172:175], v[60:63]
	v_mfma_f32_16x16x32_bf16 v[56:59], v[136:139], v[172:175], v[56:59]
	v_mfma_f32_16x16x32_bf16 v[44:47], v[120:123], v[198:201], v[44:47]
	v_mfma_f32_16x16x32_bf16 v[40:43], v[136:139], v[198:201], v[40:43]
	v_mfma_f32_16x16x32_bf16 v[28:31], v[120:123], v[212:215], v[28:31]
	v_mfma_f32_16x16x32_bf16 v[24:27], v[136:139], v[212:215], v[24:27]
	v_mfma_f32_16x16x32_bf16 v[12:15], v[120:123], v[220:223], v[12:15]
	v_mfma_f32_16x16x32_bf16 v[8:11], v[136:139], v[220:223], v[8:11]
	v_mfma_f32_16x16x32_bf16 v[60:63], v[132:135], v[194:197], v[60:63]
	v_mfma_f32_16x16x32_bf16 v[56:59], v[140:143], v[194:197], v[56:59]
	v_mfma_f32_16x16x32_bf16 v[44:47], v[132:135], v[208:211], v[44:47]
	v_mfma_f32_16x16x32_bf16 v[40:43], v[140:143], v[208:211], v[40:43]
	v_mfma_f32_16x16x32_bf16 v[28:31], v[132:135], v[216:219], v[28:31]
	v_mfma_f32_16x16x32_bf16 v[24:27], v[140:143], v[216:219], v[24:27]
	v_mfma_f32_16x16x32_bf16 v[12:15], v[132:135], v[224:227], v[12:15]
	v_mfma_f32_16x16x32_bf16 v[8:11], v[140:143], v[224:227], v[8:11]
	v_mfma_f32_16x16x32_bf16 v[52:55], v[144:147], v[172:175], v[52:55]
	v_mfma_f32_16x16x32_bf16 v[48:51], v[152:155], v[172:175], v[48:51]
	v_mfma_f32_16x16x32_bf16 v[36:39], v[144:147], v[198:201], v[36:39]
	v_mfma_f32_16x16x32_bf16 v[32:35], v[152:155], v[198:201], v[32:35]
	v_mfma_f32_16x16x32_bf16 v[20:23], v[144:147], v[212:215], v[20:23]
	v_mfma_f32_16x16x32_bf16 v[16:19], v[152:155], v[212:215], v[16:19]
	v_mfma_f32_16x16x32_bf16 v[4:7], v[144:147], v[220:223], v[4:7]
	v_mfma_f32_16x16x32_bf16 v[0:3], v[152:155], v[220:223], v[0:3]
	v_mfma_f32_16x16x32_bf16 v[52:55], v[148:151], v[194:197], v[52:55]
	v_mfma_f32_16x16x32_bf16 v[48:51], v[168:171], v[194:197], v[48:51]
	v_mfma_f32_16x16x32_bf16 v[36:39], v[148:151], v[208:211], v[36:39]
	v_mfma_f32_16x16x32_bf16 v[32:35], v[168:171], v[208:211], v[32:35]
	v_mfma_f32_16x16x32_bf16 v[20:23], v[148:151], v[216:219], v[20:23]
	v_mfma_f32_16x16x32_bf16 v[16:19], v[168:171], v[216:219], v[16:19]
	v_mfma_f32_16x16x32_bf16 v[4:7], v[148:151], v[224:227], v[4:7]
	v_mfma_f32_16x16x32_bf16 v[0:3], v[168:171], v[224:227], v[0:3]
	s_barrier
	s_add_i32 s59, s59, 2
	s_add_u32 s51, s51, 0x100
	s_addc_u32 s58, s58, 0
	s_add_u32 s4, s4, 0x100
	s_addc_u32 s5, s5, 0
	s_cmp_gt_u32 s59, 61
	s_cbranch_scc0 .LBB0_744
	s_setprio 0
	s_and_b64 vcc, exec, s[42:43]
	s_cbranch_vccz .LBB0_747
	s_barrier
